# peeled first k-iteration with SrcC=0 (no accumulator zeroing at tile boundaries) on top of best
# baseline (speedup 1.0000x reference)
; #define PG8_STAGE(bufoff, gbase, voff) do { _Pragma("unroll") for (int _i = 0; _i < 2; ++_i) \
;         __builtin_amdgcn_global_load_lds((const unsigned*)((const char*)(gbase) + (voff)[_i]), (PG8_LAS unsigned*)(lds + (bufoff) + ldsw + _i * 8192), 16, 0, 0); } while (0)
; #define PG8_LDA(dst, b, h) do { _Pragma("unroll") for (int m = 0; m < 4; ++m) _Pragma("unroll") for (int k = 0; k < 2; ++k) dst[m][k] = *(const PG8_LAS bf16x8*)(lds + PG8_SA(b, h) + aoff + m * 2048 + k * 1024); } while (0)
; #define PG8_LDB(dst, b, h) do { _Pragma("unroll") for (int n = 0; n < 2; ++n) _Pragma("unroll") for (int k = 0; k < 2; ++k) dst[n][k] = *(const PG8_LAS bf16x8*)(lds + PG8_SB(b, h) + boff + n * 2048 + k * 1024); } while (0)
; #define PG8_MMA(ai, bj, At, Bt) do { __builtin_amdgcn_s_setprio(1); _Pragma("unroll") for (int m = 0; m < 4; ++m) _Pragma("unroll") for (int n = 0; n < 2; ++n) _Pragma("unroll") for (int k = 0; k < 2; ++k) \
;         acc[ai][bj][m][n] = __builtin_amdgcn_mfma_f32_16x16x32_bf16(Bt[n][k], At[m][k], acc[ai][bj][m][n], 0, 0, 0); __builtin_amdgcn_s_setprio(0); } while (0)
; template <class Epi, class Sched, bool ALIGN_EPI = false, bool SP2 = false>
; __device__ __forceinline__ void gemm_phase(PG8_LAS unsigned char* lds, const Gemm g, const Sched& S, const Epi& E) {
;     ...
;         const char* nA = has_next ? (const char*)g.A + (size_t)nxt.pm * tstepA + (size_t)((nxt.pn >> g.a_shift) * g.a_stride) : cA; const char* nB = has_next ? (const char*)g.Bt + (size_t)nxt.pn * tstepB : cB;
; #pragma clang loop unroll(disable)
;         for (int t = 0; t < nt; t += 2) {
;             const bool last = (t == nt - 2);
;             const char* a1 = cA + (size_t)(t + 1) * kstep;
;             const char* a2 = last ? nA : cA + (size_t)(t + 2) * kstep; const char* b2 = last ? nB : cB + (size_t)(t + 2) * kstep;
;             const char* a3 = a2 + kstep; const char* b3 = b2 + kstep;
;             if (last && has_next) S.a_ready(nxt);
;             if constexpr (SP2) {
;             PG8_LDB(B0, 0, 0); PG8_LDB(B1, 0, 1); PG8_SCHED; PG8_LDA(At, 0, 0); PG8_STAGE(PG8_SA(1, 1), a1 + hstepA, voffA);
;             PG8_WAIT_V(8); PG8_WAIT_L(0); PG8_BAR; PG8_MMA(0, 0, At, B0); PG8_MMA(0, 1, At, B1); PG8_BAR; PG8_SCHED;
;             PG8_LDA(At, 0, 1); PG8_STAGE(PG8_SB(0, 0), b2, voffB); PG8_STAGE(PG8_SB(0, 1), b2 + hstepB, voffB); PG8_STAGE(PG8_SA(0, 0), a2, voffA);
.LBB0_364:
	s_ashr_i32 s21, s20, 31
	s_lshl_b64 s[10:11], s[20:21], 21
	s_add_u32 s22, s54, s10
	s_addc_u32 s23, s55, s11
	s_and_b64 s[10:11], s[6:7], exec
	s_cselect_b32 s9, s23, s61
	s_cselect_b32 s10, s22, s60
	s_ashr_i32 s19, s18, 31
	s_lshl_b64 s[24:25], s[18:19], 21
	s_add_u32 s56, s88, s24
	s_addc_u32 s57, s89, s25
	s_and_b64 s[24:25], s[6:7], exec
	s_cselect_b32 s11, s57, s67
	s_cselect_b32 s19, s56, s66
	s_add_u32 s60, s60, 0x100080
	s_addc_u32 s61, s61, 0
	s_add_u32 s21, s66, 0x100
	s_addc_u32 s72, s67, 0
	s_mov_b32 s73, -2
	s_waitcnt vmcnt(0)
	s_setprio 1
	s_cmp_eq_u64 s[16:17], 0
	s_cbranch_scc1 .Lsp_LBB0_365
	s_setprio 0
.Lsp_LBB0_365:
	ds_read_b128 v[154:157], v169
	ds_read_b128 v[158:161], v169 offset:1024
	ds_read_b128 v[162:165], v169 offset:2048
	ds_read_b128 v[174:177], v169 offset:3072
	ds_read_b128 v[178:181], v170
	ds_read_b128 v[182:185], v170 offset:1024
	ds_read_b128 v[186:189], v170 offset:2048
	ds_read_b128 v[190:193], v170 offset:3072
	s_add_u32 s24, s60, 0xfff00080
	s_addc_u32 s25, s61, -1
	s_cmp_eq_u32 s73, 60
	s_cselect_b32 s25, s9, s25
	s_cselect_b32 s24, s10, s24
	s_cselect_b32 s67, s11, s72
	s_cselect_b32 s66, s19, s21
	s_add_i32 m0, s27, 0xc000
	ds_read_b128 v[194:197], v171
	ds_read_b128 v[198:201], v171 offset:1024
	ds_read_b128 v[202:205], v171 offset:2048
	ds_read_b128 v[206:209], v171 offset:3072
	ds_read_b128 v[210:213], v171 offset:4096
	ds_read_b128 v[214:217], v171 offset:5120
	ds_read_b128 v[218:221], v171 offset:6144
	ds_read_b128 v[222:225], v171 offset:7168
	global_load_lds_dwordx4 v146, s[60:61]
	s_add_i32 m0, s27, 0xe000
	s_nop 0
	global_load_lds_dwordx4 v148, s[60:61]
	s_waitcnt vmcnt(8)
	s_waitcnt lgkmcnt(0)
	s_barrier
	s_waitcnt lgkmcnt(0)
	v_mfma_f32_16x16x32_bf16 v[126:129], v[154:157], v[194:197], 0
	v_mfma_f32_16x16x32_bf16 v[122:125], v[162:165], v[194:197], 0
	v_mfma_f32_16x16x32_bf16 v[110:113], v[154:157], v[202:205], 0
	v_mfma_f32_16x16x32_bf16 v[106:109], v[162:165], v[202:205], 0
	v_mfma_f32_16x16x32_bf16 v[94:97], v[154:157], v[210:213], 0
	v_mfma_f32_16x16x32_bf16 v[90:93], v[162:165], v[210:213], 0
	v_mfma_f32_16x16x32_bf16 v[78:81], v[154:157], v[218:221], 0
	v_mfma_f32_16x16x32_bf16 v[74:77], v[162:165], v[218:221], 0
	v_mfma_f32_16x16x32_bf16 v[126:129], v[158:161], v[198:201], v[126:129]
	v_mfma_f32_16x16x32_bf16 v[122:125], v[174:177], v[198:201], v[122:125]
	v_mfma_f32_16x16x32_bf16 v[110:113], v[158:161], v[206:209], v[110:113]
	v_mfma_f32_16x16x32_bf16 v[106:109], v[174:177], v[206:209], v[106:109]
	v_mfma_f32_16x16x32_bf16 v[94:97], v[158:161], v[214:217], v[94:97]
	v_mfma_f32_16x16x32_bf16 v[90:93], v[174:177], v[214:217], v[90:93]
	v_mfma_f32_16x16x32_bf16 v[78:81], v[158:161], v[222:225], v[78:81]
	v_mfma_f32_16x16x32_bf16 v[74:77], v[174:177], v[222:225], v[74:77]
	v_mfma_f32_16x16x32_bf16 v[118:121], v[178:181], v[194:197], 0
	v_mfma_f32_16x16x32_bf16 v[114:117], v[186:189], v[194:197], 0
	v_mfma_f32_16x16x32_bf16 v[102:105], v[178:181], v[202:205], 0
	v_mfma_f32_16x16x32_bf16 v[98:101], v[186:189], v[202:205], 0
	v_mfma_f32_16x16x32_bf16 v[86:89], v[178:181], v[210:213], 0
	v_mfma_f32_16x16x32_bf16 v[82:85], v[186:189], v[210:213], 0
	v_mfma_f32_16x16x32_bf16 v[70:73], v[178:181], v[218:221], 0
	v_mfma_f32_16x16x32_bf16 v[66:69], v[186:189], v[218:221], 0
	v_mfma_f32_16x16x32_bf16 v[118:121], v[182:185], v[198:201], v[118:121]
	v_mfma_f32_16x16x32_bf16 v[114:117], v[190:193], v[198:201], v[114:117]
	v_mfma_f32_16x16x32_bf16 v[102:105], v[182:185], v[206:209], v[102:105]
	v_mfma_f32_16x16x32_bf16 v[98:101], v[190:193], v[206:209], v[98:101]
	v_mfma_f32_16x16x32_bf16 v[86:89], v[182:185], v[214:217], v[86:89]
	v_mfma_f32_16x16x32_bf16 v[82:85], v[190:193], v[214:217], v[82:85]
	v_mfma_f32_16x16x32_bf16 v[70:73], v[182:185], v[222:225], v[70:73]
	v_mfma_f32_16x16x32_bf16 v[66:69], v[190:193], v[222:225], v[66:69]
	s_barrier
	s_add_i32 s74, s47, s26
	s_add_u32 s98, s66, 0x80
	s_addc_u32 s99, s67, 0
	s_add_u32 s100, s24, 0x80
	s_addc_u32 s101, s25, 0
	s_mov_b32 m0, s74
	ds_read_b128 v[194:197], v171 offset:16384
	ds_read_b128 v[198:201], v171 offset:17408
	ds_read_b128 v[202:205], v171 offset:18432
	ds_read_b128 v[206:209], v171 offset:19456
	ds_read_b128 v[210:213], v171 offset:20480
	ds_read_b128 v[214:217], v171 offset:21504
	ds_read_b128 v[218:221], v171 offset:22528
	ds_read_b128 v[222:225], v171 offset:23552
	global_load_lds_dwordx4 v132, s[66:67]
	s_add_i32 m0, s74, 0x2000
	s_add_u32 s74, s66, 0x100000
	s_addc_u32 s75, s67, 0
	s_add_i32 s76, s48, s26
	global_load_lds_dwordx4 v136, s[66:67]
	s_mov_b32 m0, s76
	s_nop 0
	global_load_lds_dwordx4 v132, s[74:75]
	s_add_i32 m0, s76, 0x2000
	s_nop 0
	global_load_lds_dwordx4 v136, s[74:75]
	s_mov_b32 m0, s27
	s_nop 0
	global_load_lds_dwordx4 v130, s[24:25]
	s_mov_b32 m0, s34
	s_nop 0
	global_load_lds_dwordx4 v134, s[24:25]
	s_waitcnt vmcnt(8)
	s_waitcnt lgkmcnt(0)
	s_barrier
; #define PG8_STAGE(bufoff, gbase, voff) do { _Pragma("unroll") for (int _i = 0; _i < 2; ++_i) \
;         __builtin_amdgcn_global_load_lds((const unsigned*)((const char*)(gbase) + (voff)[_i]), (PG8_LAS unsigned*)(lds + (bufoff) + ldsw + _i * 8192), 16, 0, 0); } while (0)
; #define PG8_LDA(dst, b, h) do { _Pragma("unroll") for (int m = 0; m < 4; ++m) _Pragma("unroll") for (int k = 0; k < 2; ++k) dst[m][k] = *(const PG8_LAS bf16x8*)(lds + PG8_SA(b, h) + aoff + m * 2048 + k * 1024); } while (0)
; #define PG8_LDB(dst, b, h) do { _Pragma("unroll") for (int n = 0; n < 2; ++n) _Pragma("unroll") for (int k = 0; k < 2; ++k) dst[n][k] = *(const PG8_LAS bf16x8*)(lds + PG8_SB(b, h) + boff + n * 2048 + k * 1024); } while (0)
; #define PG8_MMA(ai, bj, At, Bt) do { __builtin_amdgcn_s_setprio(1); _Pragma("unroll") for (int m = 0; m < 4; ++m) _Pragma("unroll") for (int n = 0; n < 2; ++n) _Pragma("unroll") for (int k = 0; k < 2; ++k) \
;         acc[ai][bj][m][n] = __builtin_amdgcn_mfma_f32_16x16x32_bf16(Bt[n][k], At[m][k], acc[ai][bj][m][n], 0, 0, 0); __builtin_amdgcn_s_setprio(0); } while (0)
; #define PG8_WAIT_V(n) asm volatile("s_waitcnt vmcnt(" #n ")" ::: "memory")
; #define PG8_WAIT_L(n) asm volatile("s_waitcnt lgkmcnt(" #n ")" ::: "memory")
; #define PG8_BAR __builtin_amdgcn_s_barrier()
; #define PG8_SCHED __builtin_amdgcn_sched_barrier(0)
; template <class Epi, class Sched, bool ALIGN_EPI = false, bool SP2 = false>
; __device__ __forceinline__ void gemm_phase(PG8_LAS unsigned char* lds, const Gemm g, const Sched& S, const Epi& E) {
;     ...
;             PG8_LDA(At, 0, 1); PG8_STAGE(PG8_SB(0, 0), b2, voffB); PG8_STAGE(PG8_SB(0, 1), b2 + hstepB, voffB); PG8_STAGE(PG8_SA(0, 0), a2, voffA);
;             PG8_WAIT_V(8); PG8_WAIT_L(0); PG8_BAR; PG8_MMA(1, 0, At, B0); PG8_MMA(1, 1, At, B1); PG8_BAR; PG8_SCHED;
;             PG8_LDB(B0, 1, 0); PG8_LDB(B1, 1, 1); PG8_SCHED; PG8_LDA(At, 1, 0); PG8_STAGE(PG8_SA(0, 1), a2 + hstepA, voffA);
;             PG8_WAIT_V(8); PG8_WAIT_L(0); PG8_BAR; PG8_MMA(0, 0, At, B0); PG8_MMA(0, 1, At, B1); PG8_BAR; PG8_SCHED;
;             PG8_LDA(At, 1, 1); PG8_STAGE(PG8_SB(1, 0), b3, voffB); PG8_STAGE(PG8_SB(1, 1), b3 + hstepB, voffB); PG8_STAGE(PG8_SA(1, 0), a3, voffA);
	s_waitcnt lgkmcnt(0)
	v_mfma_f32_16x16x32_bf16 v[62:65], v[154:157], v[194:197], 0
	v_mfma_f32_16x16x32_bf16 v[58:61], v[162:165], v[194:197], 0
	v_mfma_f32_16x16x32_bf16 v[46:49], v[154:157], v[202:205], 0
	v_mfma_f32_16x16x32_bf16 v[42:45], v[162:165], v[202:205], 0
	v_mfma_f32_16x16x32_bf16 v[30:33], v[154:157], v[210:213], 0
	v_mfma_f32_16x16x32_bf16 v[26:29], v[162:165], v[210:213], 0
	v_mfma_f32_16x16x32_bf16 v[14:17], v[154:157], v[218:221], 0
	v_mfma_f32_16x16x32_bf16 v[10:13], v[162:165], v[218:221], 0
	v_mfma_f32_16x16x32_bf16 v[62:65], v[158:161], v[198:201], v[62:65]
	v_mfma_f32_16x16x32_bf16 v[58:61], v[174:177], v[198:201], v[58:61]
	v_mfma_f32_16x16x32_bf16 v[46:49], v[158:161], v[206:209], v[46:49]
	v_mfma_f32_16x16x32_bf16 v[42:45], v[174:177], v[206:209], v[42:45]
	v_mfma_f32_16x16x32_bf16 v[30:33], v[158:161], v[214:217], v[30:33]
	v_mfma_f32_16x16x32_bf16 v[26:29], v[174:177], v[214:217], v[26:29]
	v_mfma_f32_16x16x32_bf16 v[14:17], v[158:161], v[222:225], v[14:17]
	v_mfma_f32_16x16x32_bf16 v[10:13], v[174:177], v[222:225], v[10:13]
	v_mfma_f32_16x16x32_bf16 v[54:57], v[178:181], v[194:197], 0
	v_mfma_f32_16x16x32_bf16 v[50:53], v[186:189], v[194:197], 0
	v_mfma_f32_16x16x32_bf16 v[38:41], v[178:181], v[202:205], 0
	v_mfma_f32_16x16x32_bf16 v[34:37], v[186:189], v[202:205], 0
	v_mfma_f32_16x16x32_bf16 v[22:25], v[178:181], v[210:213], 0
	v_mfma_f32_16x16x32_bf16 v[18:21], v[186:189], v[210:213], 0
	v_mfma_f32_16x16x32_bf16 v[6:9], v[178:181], v[218:221], 0
	v_mfma_f32_16x16x32_bf16 v[2:5], v[186:189], v[218:221], 0
	v_mfma_f32_16x16x32_bf16 v[54:57], v[182:185], v[198:201], v[54:57]
	v_mfma_f32_16x16x32_bf16 v[50:53], v[190:193], v[198:201], v[50:53]
	v_mfma_f32_16x16x32_bf16 v[38:41], v[182:185], v[206:209], v[38:41]
	v_mfma_f32_16x16x32_bf16 v[34:37], v[190:193], v[206:209], v[34:37]
	v_mfma_f32_16x16x32_bf16 v[22:25], v[182:185], v[214:217], v[22:25]
	v_mfma_f32_16x16x32_bf16 v[18:21], v[190:193], v[214:217], v[18:21]
	v_mfma_f32_16x16x32_bf16 v[6:9], v[182:185], v[222:225], v[6:9]
	v_mfma_f32_16x16x32_bf16 v[2:5], v[190:193], v[222:225], v[2:5]
	s_barrier
	s_add_i32 s74, 0, 0x18000
	v_add_u32_e32 v138, s74, v141
	s_add_i32 s75, 0, 0x1c000
	ds_read_b128 v[154:157], v138
	ds_read_b128 v[158:161], v138 offset:1024
	ds_read_b128 v[162:165], v138 offset:2048
	ds_read_b128 v[174:177], v138 offset:3072
	v_add_u32_e32 v138, s75, v141
	ds_read_b128 v[178:181], v138
	ds_read_b128 v[182:185], v138 offset:1024
	ds_read_b128 v[186:189], v138 offset:2048
	ds_read_b128 v[190:193], v138 offset:3072
	s_add_u32 s24, s24, 0x100000
	s_addc_u32 s25, s25, 0
	s_mov_b32 m0, s35
	ds_read_b128 v[194:197], v171 offset:32768
	ds_read_b128 v[198:201], v171 offset:33792
	ds_read_b128 v[202:205], v171 offset:34816
	ds_read_b128 v[206:209], v171 offset:35840
	ds_read_b128 v[210:213], v171 offset:36864
	ds_read_b128 v[214:217], v171 offset:37888
	ds_read_b128 v[218:221], v171 offset:38912
	ds_read_b128 v[222:225], v171 offset:39936
	global_load_lds_dwordx4 v130, s[24:25]
	s_mov_b32 m0, s36
	s_nop 0
	global_load_lds_dwordx4 v134, s[24:25]
	s_waitcnt vmcnt(8)
	s_waitcnt lgkmcnt(0)
	s_barrier
	s_waitcnt lgkmcnt(0)
	v_mfma_f32_16x16x32_bf16 v[126:129], v[154:157], v[194:197], v[126:129]
	v_mfma_f32_16x16x32_bf16 v[122:125], v[162:165], v[194:197], v[122:125]
	v_mfma_f32_16x16x32_bf16 v[110:113], v[154:157], v[202:205], v[110:113]
	v_mfma_f32_16x16x32_bf16 v[106:109], v[162:165], v[202:205], v[106:109]
	v_mfma_f32_16x16x32_bf16 v[94:97], v[154:157], v[210:213], v[94:97]
	v_mfma_f32_16x16x32_bf16 v[90:93], v[162:165], v[210:213], v[90:93]
	v_mfma_f32_16x16x32_bf16 v[78:81], v[154:157], v[218:221], v[78:81]
	v_mfma_f32_16x16x32_bf16 v[74:77], v[162:165], v[218:221], v[74:77]
	v_mfma_f32_16x16x32_bf16 v[126:129], v[158:161], v[198:201], v[126:129]
	v_mfma_f32_16x16x32_bf16 v[122:125], v[174:177], v[198:201], v[122:125]
	v_mfma_f32_16x16x32_bf16 v[110:113], v[158:161], v[206:209], v[110:113]
	v_mfma_f32_16x16x32_bf16 v[106:109], v[174:177], v[206:209], v[106:109]
	v_mfma_f32_16x16x32_bf16 v[94:97], v[158:161], v[214:217], v[94:97]
	v_mfma_f32_16x16x32_bf16 v[90:93], v[174:177], v[214:217], v[90:93]
	v_mfma_f32_16x16x32_bf16 v[78:81], v[158:161], v[222:225], v[78:81]
	v_mfma_f32_16x16x32_bf16 v[74:77], v[174:177], v[222:225], v[74:77]
	v_mfma_f32_16x16x32_bf16 v[118:121], v[178:181], v[194:197], v[118:121]
	v_mfma_f32_16x16x32_bf16 v[114:117], v[186:189], v[194:197], v[114:117]
	v_mfma_f32_16x16x32_bf16 v[102:105], v[178:181], v[202:205], v[102:105]
	v_mfma_f32_16x16x32_bf16 v[98:101], v[186:189], v[202:205], v[98:101]
	v_mfma_f32_16x16x32_bf16 v[86:89], v[178:181], v[210:213], v[86:89]
	v_mfma_f32_16x16x32_bf16 v[82:85], v[186:189], v[210:213], v[82:85]
	v_mfma_f32_16x16x32_bf16 v[70:73], v[178:181], v[218:221], v[70:73]
	v_mfma_f32_16x16x32_bf16 v[66:69], v[186:189], v[218:221], v[66:69]
	v_mfma_f32_16x16x32_bf16 v[118:121], v[182:185], v[198:201], v[118:121]
	v_mfma_f32_16x16x32_bf16 v[114:117], v[190:193], v[198:201], v[114:117]
	v_mfma_f32_16x16x32_bf16 v[102:105], v[182:185], v[206:209], v[102:105]
	v_mfma_f32_16x16x32_bf16 v[98:101], v[190:193], v[206:209], v[98:101]
	v_mfma_f32_16x16x32_bf16 v[86:89], v[182:185], v[214:217], v[86:89]
	v_mfma_f32_16x16x32_bf16 v[82:85], v[190:193], v[214:217], v[82:85]
	v_mfma_f32_16x16x32_bf16 v[70:73], v[182:185], v[222:225], v[70:73]
	v_mfma_f32_16x16x32_bf16 v[66:69], v[190:193], v[222:225], v[66:69]
	s_barrier
; #define PG8_STAGE(bufoff, gbase, voff) do { _Pragma("unroll") for (int _i = 0; _i < 2; ++_i) \
;         __builtin_amdgcn_global_load_lds((const unsigned*)((const char*)(gbase) + (voff)[_i]), (PG8_LAS unsigned*)(lds + (bufoff) + ldsw + _i * 8192), 16, 0, 0); } while (0)
; #define PG8_LDA(dst, b, h) do { _Pragma("unroll") for (int m = 0; m < 4; ++m) _Pragma("unroll") for (int k = 0; k < 2; ++k) dst[m][k] = *(const PG8_LAS bf16x8*)(lds + PG8_SA(b, h) + aoff + m * 2048 + k * 1024); } while (0)
; #define PG8_MMA(ai, bj, At, Bt) do { __builtin_amdgcn_s_setprio(1); _Pragma("unroll") for (int m = 0; m < 4; ++m) _Pragma("unroll") for (int n = 0; n < 2; ++n) _Pragma("unroll") for (int k = 0; k < 2; ++k) \
;         acc[ai][bj][m][n] = __builtin_amdgcn_mfma_f32_16x16x32_bf16(Bt[n][k], At[m][k], acc[ai][bj][m][n], 0, 0, 0); __builtin_amdgcn_s_setprio(0); } while (0)
; #define PG8_WAIT_V(n) asm volatile("s_waitcnt vmcnt(" #n ")" ::: "memory")
; #define PG8_WAIT_L(n) asm volatile("s_waitcnt lgkmcnt(" #n ")" ::: "memory")
; #define PG8_BAR __builtin_amdgcn_s_barrier()
; #define PG8_SCHED __builtin_amdgcn_sched_barrier(0)
; template <class Epi, class Sched, bool ALIGN_EPI = false, bool SP2 = false>
; __device__ __forceinline__ void gemm_phase(PG8_LAS unsigned char* lds, const Gemm g, const Sched& S, const Epi& E) {
;     ...
;             PG8_LDA(At, 1, 1); PG8_STAGE(PG8_SB(1, 0), b3, voffB); PG8_STAGE(PG8_SB(1, 1), b3 + hstepB, voffB); PG8_STAGE(PG8_SA(1, 0), a3, voffA);
;             PG8_WAIT_V(8); PG8_WAIT_L(0); PG8_BAR; PG8_MMA(1, 0, At, B0); PG8_MMA(1, 1, At, B1); PG8_BAR; PG8_SCHED;
	s_add_i32 s24, s74, s26
	s_mov_b32 m0, s24
	ds_read_b128 v[194:197], v171 offset:49152
	ds_read_b128 v[198:201], v171 offset:50176
	ds_read_b128 v[202:205], v171 offset:51200
	ds_read_b128 v[206:209], v171 offset:52224
	ds_read_b128 v[210:213], v171 offset:53248
	ds_read_b128 v[214:217], v171 offset:54272
	ds_read_b128 v[218:221], v171 offset:55296
	ds_read_b128 v[222:225], v171 offset:56320
	global_load_lds_dwordx4 v132, s[98:99]
	s_add_i32 m0, s24, 0x2000
	s_add_u32 s24, s66, 0x100080
	s_addc_u32 s25, s67, 0
	s_add_i32 s66, s75, s26
	global_load_lds_dwordx4 v136, s[98:99]
	s_mov_b32 m0, s66
	s_nop 0
	global_load_lds_dwordx4 v132, s[24:25]
	s_add_i32 m0, s66, 0x2000
	s_nop 0
	global_load_lds_dwordx4 v136, s[24:25]
	s_mov_b32 m0, s42
	s_nop 0
	global_load_lds_dwordx4 v130, s[100:101]
	s_mov_b32 m0, s43
	s_nop 0
	global_load_lds_dwordx4 v134, s[100:101]
	s_waitcnt vmcnt(8)
	s_waitcnt lgkmcnt(0)
	s_barrier
	s_waitcnt lgkmcnt(0)
	v_mfma_f32_16x16x32_bf16 v[62:65], v[154:157], v[194:197], v[62:65]
	v_mfma_f32_16x16x32_bf16 v[58:61], v[162:165], v[194:197], v[58:61]
	v_mfma_f32_16x16x32_bf16 v[46:49], v[154:157], v[202:205], v[46:49]
	v_mfma_f32_16x16x32_bf16 v[42:45], v[162:165], v[202:205], v[42:45]
	v_mfma_f32_16x16x32_bf16 v[30:33], v[154:157], v[210:213], v[30:33]
	v_mfma_f32_16x16x32_bf16 v[26:29], v[162:165], v[210:213], v[26:29]
	v_mfma_f32_16x16x32_bf16 v[14:17], v[154:157], v[218:221], v[14:17]
	v_mfma_f32_16x16x32_bf16 v[10:13], v[162:165], v[218:221], v[10:13]
	v_mfma_f32_16x16x32_bf16 v[62:65], v[158:161], v[198:201], v[62:65]
	v_mfma_f32_16x16x32_bf16 v[58:61], v[174:177], v[198:201], v[58:61]
	v_mfma_f32_16x16x32_bf16 v[46:49], v[158:161], v[206:209], v[46:49]
	v_mfma_f32_16x16x32_bf16 v[42:45], v[174:177], v[206:209], v[42:45]
	v_mfma_f32_16x16x32_bf16 v[30:33], v[158:161], v[214:217], v[30:33]
	v_mfma_f32_16x16x32_bf16 v[26:29], v[174:177], v[214:217], v[26:29]
	v_mfma_f32_16x16x32_bf16 v[14:17], v[158:161], v[222:225], v[14:17]
	v_mfma_f32_16x16x32_bf16 v[10:13], v[174:177], v[222:225], v[10:13]
	v_mfma_f32_16x16x32_bf16 v[54:57], v[178:181], v[194:197], v[54:57]
	v_mfma_f32_16x16x32_bf16 v[50:53], v[186:189], v[194:197], v[50:53]
	v_mfma_f32_16x16x32_bf16 v[38:41], v[178:181], v[202:205], v[38:41]
	v_mfma_f32_16x16x32_bf16 v[34:37], v[186:189], v[202:205], v[34:37]
	v_mfma_f32_16x16x32_bf16 v[22:25], v[178:181], v[210:213], v[22:25]
	v_mfma_f32_16x16x32_bf16 v[18:21], v[186:189], v[210:213], v[18:21]
	v_mfma_f32_16x16x32_bf16 v[6:9], v[178:181], v[218:221], v[6:9]
	v_mfma_f32_16x16x32_bf16 v[2:5], v[186:189], v[218:221], v[2:5]
	v_mfma_f32_16x16x32_bf16 v[54:57], v[182:185], v[198:201], v[54:57]
	v_mfma_f32_16x16x32_bf16 v[50:53], v[190:193], v[198:201], v[50:53]
	v_mfma_f32_16x16x32_bf16 v[38:41], v[182:185], v[206:209], v[38:41]
	v_mfma_f32_16x16x32_bf16 v[34:37], v[190:193], v[206:209], v[34:37]
	v_mfma_f32_16x16x32_bf16 v[22:25], v[182:185], v[214:217], v[22:25]
	v_mfma_f32_16x16x32_bf16 v[18:21], v[190:193], v[214:217], v[18:21]
	v_mfma_f32_16x16x32_bf16 v[6:9], v[182:185], v[222:225], v[6:9]
	v_mfma_f32_16x16x32_bf16 v[2:5], v[190:193], v[222:225], v[2:5]
	s_barrier
	s_add_i32 s73, s73, 2
	s_add_u32 s60, s60, 0x100
	s_addc_u32 s61, s61, 0
	s_add_u32 s21, s21, 0x100
	s_addc_u32 s72, s72, 0
	s_cmp_gt_u32 s73, 61

; #define PG8_STAGE(bufoff, gbase, voff) do { _Pragma("unroll") for (int _i = 0; _i < 2; ++_i) \
;         __builtin_amdgcn_global_load_lds((const unsigned*)((const char*)(gbase) + (voff)[_i]), (PG8_LAS unsigned*)(lds + (bufoff) + ldsw + _i * 8192), 16, 0, 0); } while (0)
; #define PG8_LDA(dst, b, h) do { _Pragma("unroll") for (int m = 0; m < 4; ++m) _Pragma("unroll") for (int k = 0; k < 2; ++k) dst[m][k] = *(const PG8_LAS bf16x8*)(lds + PG8_SA(b, h) + aoff + m * 2048 + k * 1024); } while (0)
; #define PG8_LDB(dst, b, h) do { _Pragma("unroll") for (int n = 0; n < 2; ++n) _Pragma("unroll") for (int k = 0; k < 2; ++k) dst[n][k] = *(const PG8_LAS bf16x8*)(lds + PG8_SB(b, h) + boff + n * 2048 + k * 1024); } while (0)
; #define PG8_MMA(ai, bj, At, Bt) do { __builtin_amdgcn_s_setprio(1); _Pragma("unroll") for (int m = 0; m < 4; ++m) _Pragma("unroll") for (int n = 0; n < 2; ++n) _Pragma("unroll") for (int k = 0; k < 2; ++k) \
;         acc[ai][bj][m][n] = __builtin_amdgcn_mfma_f32_16x16x32_bf16(Bt[n][k], At[m][k], acc[ai][bj][m][n], 0, 0, 0); __builtin_amdgcn_s_setprio(0); } while (0)
; template <class Epi, class Sched, bool ALIGN_EPI = false, bool SP2 = false>
; __device__ __forceinline__ void gemm_phase(PG8_LAS unsigned char* lds, const Gemm g, const Sched& S, const Epi& E) {
;     ...
;         const char* nA = has_next ? (const char*)g.A + (size_t)nxt.pm * tstepA + (size_t)((nxt.pn >> g.a_shift) * g.a_stride) : cA; const char* nB = has_next ? (const char*)g.Bt + (size_t)nxt.pn * tstepB : cB;
; #pragma clang loop unroll(disable)
;         for (int t = 0; t < nt; t += 2) {
;             const bool last = (t == nt - 2);
;             const char* a1 = cA + (size_t)(t + 1) * kstep;
;             const char* a2 = last ? nA : cA + (size_t)(t + 2) * kstep; const char* b2 = last ? nB : cB + (size_t)(t + 2) * kstep;
;             const char* a3 = a2 + kstep; const char* b3 = b2 + kstep;
;             if (last && has_next) S.a_ready(nxt);
;             if constexpr (SP2) {
;             PG8_LDB(B0, 0, 0); PG8_LDB(B1, 0, 1); PG8_SCHED; PG8_LDA(At, 0, 0); PG8_STAGE(PG8_SA(1, 1), a1 + hstepA, voffA);
;             PG8_WAIT_V(8); PG8_WAIT_L(0); PG8_BAR; PG8_MMA(0, 0, At, B0); PG8_MMA(0, 1, At, B1); PG8_BAR; PG8_SCHED;
;             PG8_LDA(At, 0, 1); PG8_STAGE(PG8_SB(0, 0), b2, voffB); PG8_STAGE(PG8_SB(0, 1), b2 + hstepB, voffB); PG8_STAGE(PG8_SA(0, 0), a2, voffA);
.LBB0_838:
	s_ashr_i32 s17, s16, 31
	s_lshl_b64 s[18:19], s[16:17], 21
	s_add_u32 s18, s31, s18
	s_addc_u32 s19, s58, s19
	s_and_b64 s[20:21], s[4:5], exec
	s_cselect_b32 s17, s19, s37
	s_cselect_b32 s49, s18, s36
	s_ashr_i32 s15, s14, 31
	s_lshl_b64 s[20:21], s[14:15], 21
	v_readlane_b32 s24, v254, 38
	v_readlane_b32 s25, v254, 39
	s_add_u32 s20, s24, s20
	s_addc_u32 s21, s25, s21
	s_and_b64 s[24:25], s[4:5], exec
	s_cselect_b32 s15, s21, s39
	s_cselect_b32 s62, s20, s38
	s_add_u32 s36, s36, 0x100080
	s_addc_u32 s37, s37, 0
	s_add_u32 s63, s38, 0x100
	s_addc_u32 s68, s39, 0
	s_mov_b32 s69, -2
	s_setprio 1
	s_cmp_eq_u64 s[10:11], 0
	s_cbranch_scc1 .Lsp_LBB0_839
	s_setprio 0
.Lsp_LBB0_839:
	ds_read_b128 v[130:133], v166
	ds_read_b128 v[134:137], v166 offset:1024
	ds_read_b128 v[138:141], v166 offset:2048
	ds_read_b128 v[142:145], v166 offset:3072
	ds_read_b128 v[170:173], v167
	ds_read_b128 v[174:177], v167 offset:1024
	ds_read_b128 v[178:181], v167 offset:2048
	ds_read_b128 v[182:185], v167 offset:3072
	s_add_u32 s24, s36, 0xfff00080
	s_addc_u32 s25, s37, -1
	s_cmp_eq_u32 s69, 60
	s_cselect_b32 s25, s17, s25
	s_cselect_b32 s24, s49, s24
	s_cselect_b32 s39, s15, s68
	s_cselect_b32 s38, s62, s63
	s_add_i32 m0, s23, 0xc000
	ds_read_b128 v[186:189], v168
	ds_read_b128 v[190:193], v168 offset:1024
	ds_read_b128 v[194:197], v168 offset:2048
	ds_read_b128 v[198:201], v168 offset:3072
	ds_read_b128 v[202:205], v168 offset:4096
	ds_read_b128 v[206:209], v168 offset:5120
	ds_read_b128 v[210:213], v168 offset:6144
	ds_read_b128 v[214:217], v168 offset:7168
	global_load_lds_dwordx4 v154, s[36:37]
	s_add_i32 m0, s23, 0xe000
	s_nop 0
	global_load_lds_dwordx4 v156, s[36:37]
	s_waitcnt vmcnt(8)
	s_waitcnt lgkmcnt(0)
	s_barrier
	s_waitcnt lgkmcnt(0)
	v_mfma_f32_16x16x32_bf16 v[126:129], v[130:133], v[186:189], 0
	v_mfma_f32_16x16x32_bf16 v[122:125], v[138:141], v[186:189], 0
	v_mfma_f32_16x16x32_bf16 v[118:121], v[130:133], v[194:197], 0
	v_mfma_f32_16x16x32_bf16 v[114:117], v[138:141], v[194:197], 0
	v_mfma_f32_16x16x32_bf16 v[110:113], v[130:133], v[202:205], 0
	v_mfma_f32_16x16x32_bf16 v[102:105], v[138:141], v[202:205], 0
	v_mfma_f32_16x16x32_bf16 v[94:97], v[130:133], v[210:213], 0
	v_mfma_f32_16x16x32_bf16 v[86:89], v[138:141], v[210:213], 0
	v_mfma_f32_16x16x32_bf16 v[126:129], v[134:137], v[190:193], v[126:129]
	v_mfma_f32_16x16x32_bf16 v[122:125], v[142:145], v[190:193], v[122:125]
	v_mfma_f32_16x16x32_bf16 v[118:121], v[134:137], v[198:201], v[118:121]
	v_mfma_f32_16x16x32_bf16 v[114:117], v[142:145], v[198:201], v[114:117]
	v_mfma_f32_16x16x32_bf16 v[110:113], v[134:137], v[206:209], v[110:113]
	v_mfma_f32_16x16x32_bf16 v[102:105], v[142:145], v[206:209], v[102:105]
	v_mfma_f32_16x16x32_bf16 v[94:97], v[134:137], v[214:217], v[94:97]
	v_mfma_f32_16x16x32_bf16 v[86:89], v[142:145], v[214:217], v[86:89]
	v_mfma_f32_16x16x32_bf16 v[106:109], v[170:173], v[186:189], 0
	v_mfma_f32_16x16x32_bf16 v[98:101], v[178:181], v[186:189], 0
	v_mfma_f32_16x16x32_bf16 v[90:93], v[170:173], v[194:197], 0
	v_mfma_f32_16x16x32_bf16 v[82:85], v[178:181], v[194:197], 0
	v_mfma_f32_16x16x32_bf16 v[78:81], v[170:173], v[202:205], 0
	v_mfma_f32_16x16x32_bf16 v[74:77], v[178:181], v[202:205], 0
	v_mfma_f32_16x16x32_bf16 v[70:73], v[170:173], v[210:213], 0
	v_mfma_f32_16x16x32_bf16 v[66:69], v[178:181], v[210:213], 0
	v_mfma_f32_16x16x32_bf16 v[106:109], v[174:177], v[190:193], v[106:109]
	v_mfma_f32_16x16x32_bf16 v[98:101], v[182:185], v[190:193], v[98:101]
	v_mfma_f32_16x16x32_bf16 v[90:93], v[174:177], v[198:201], v[90:93]
	v_mfma_f32_16x16x32_bf16 v[82:85], v[182:185], v[198:201], v[82:85]
	v_mfma_f32_16x16x32_bf16 v[78:81], v[174:177], v[206:209], v[78:81]
	v_mfma_f32_16x16x32_bf16 v[74:77], v[182:185], v[206:209], v[74:77]
	v_mfma_f32_16x16x32_bf16 v[70:73], v[174:177], v[214:217], v[70:73]
	v_mfma_f32_16x16x32_bf16 v[66:69], v[182:185], v[214:217], v[66:69]
	s_barrier
	s_add_i32 s72, s45, s26
	s_add_u32 s98, s38, 0x80
	s_addc_u32 s99, s39, 0
	s_add_u32 s100, s24, 0x80
	s_addc_u32 s101, s25, 0
	s_mov_b32 m0, s72
	ds_read_b128 v[186:189], v168 offset:16384
	ds_read_b128 v[190:193], v168 offset:17408
	ds_read_b128 v[194:197], v168 offset:18432
	ds_read_b128 v[198:201], v168 offset:19456
	ds_read_b128 v[202:205], v168 offset:20480
	ds_read_b128 v[206:209], v168 offset:21504
	ds_read_b128 v[210:213], v168 offset:22528
	ds_read_b128 v[214:217], v168 offset:23552
	global_load_lds_dwordx4 v150, s[38:39]
	s_add_i32 m0, s72, 0x2000
	s_add_u32 s72, s38, 0x100000
	s_addc_u32 s73, s39, 0
	s_add_i32 s74, s46, s26
	global_load_lds_dwordx4 v146, s[38:39]
	s_mov_b32 m0, s74
	s_nop 0
	global_load_lds_dwordx4 v150, s[72:73]
	s_add_i32 m0, s74, 0x2000
	s_nop 0
	global_load_lds_dwordx4 v146, s[72:73]
	s_mov_b32 m0, s23
	s_nop 0
	global_load_lds_dwordx4 v152, s[24:25]
	s_mov_b32 m0, s27
	s_nop 0
	global_load_lds_dwordx4 v148, s[24:25]
	s_waitcnt vmcnt(8)
	s_waitcnt lgkmcnt(0)
	s_barrier
; #define PG8_STAGE(bufoff, gbase, voff) do { _Pragma("unroll") for (int _i = 0; _i < 2; ++_i) \
;         __builtin_amdgcn_global_load_lds((const unsigned*)((const char*)(gbase) + (voff)[_i]), (PG8_LAS unsigned*)(lds + (bufoff) + ldsw + _i * 8192), 16, 0, 0); } while (0)
; #define PG8_LDA(dst, b, h) do { _Pragma("unroll") for (int m = 0; m < 4; ++m) _Pragma("unroll") for (int k = 0; k < 2; ++k) dst[m][k] = *(const PG8_LAS bf16x8*)(lds + PG8_SA(b, h) + aoff + m * 2048 + k * 1024); } while (0)
; #define PG8_LDB(dst, b, h) do { _Pragma("unroll") for (int n = 0; n < 2; ++n) _Pragma("unroll") for (int k = 0; k < 2; ++k) dst[n][k] = *(const PG8_LAS bf16x8*)(lds + PG8_SB(b, h) + boff + n * 2048 + k * 1024); } while (0)
; #define PG8_MMA(ai, bj, At, Bt) do { __builtin_amdgcn_s_setprio(1); _Pragma("unroll") for (int m = 0; m < 4; ++m) _Pragma("unroll") for (int n = 0; n < 2; ++n) _Pragma("unroll") for (int k = 0; k < 2; ++k) \
;         acc[ai][bj][m][n] = __builtin_amdgcn_mfma_f32_16x16x32_bf16(Bt[n][k], At[m][k], acc[ai][bj][m][n], 0, 0, 0); __builtin_amdgcn_s_setprio(0); } while (0)
; #define PG8_WAIT_V(n) asm volatile("s_waitcnt vmcnt(" #n ")" ::: "memory")
; #define PG8_WAIT_L(n) asm volatile("s_waitcnt lgkmcnt(" #n ")" ::: "memory")
; #define PG8_BAR __builtin_amdgcn_s_barrier()
; #define PG8_SCHED __builtin_amdgcn_sched_barrier(0)
; template <class Epi, class Sched, bool ALIGN_EPI = false, bool SP2 = false>
; __device__ __forceinline__ void gemm_phase(PG8_LAS unsigned char* lds, const Gemm g, const Sched& S, const Epi& E) {
;     ...
;             PG8_LDA(At, 0, 1); PG8_STAGE(PG8_SB(0, 0), b2, voffB); PG8_STAGE(PG8_SB(0, 1), b2 + hstepB, voffB); PG8_STAGE(PG8_SA(0, 0), a2, voffA);
;             PG8_WAIT_V(8); PG8_WAIT_L(0); PG8_BAR; PG8_MMA(1, 0, At, B0); PG8_MMA(1, 1, At, B1); PG8_BAR; PG8_SCHED;
;             PG8_LDB(B0, 1, 0); PG8_LDB(B1, 1, 1); PG8_SCHED; PG8_LDA(At, 1, 0); PG8_STAGE(PG8_SA(0, 1), a2 + hstepA, voffA);
;             PG8_WAIT_V(8); PG8_WAIT_L(0); PG8_BAR; PG8_MMA(0, 0, At, B0); PG8_MMA(0, 1, At, B1); PG8_BAR; PG8_SCHED;
;             PG8_LDA(At, 1, 1); PG8_STAGE(PG8_SB(1, 0), b3, voffB); PG8_STAGE(PG8_SB(1, 1), b3 + hstepB, voffB); PG8_STAGE(PG8_SA(1, 0), a3, voffA);
	s_waitcnt lgkmcnt(0)
	v_mfma_f32_16x16x32_bf16 v[62:65], v[130:133], v[186:189], 0
	v_mfma_f32_16x16x32_bf16 v[58:61], v[138:141], v[186:189], 0
	v_mfma_f32_16x16x32_bf16 v[50:53], v[130:133], v[194:197], 0
	v_mfma_f32_16x16x32_bf16 v[42:45], v[138:141], v[194:197], 0
	v_mfma_f32_16x16x32_bf16 v[34:37], v[130:133], v[202:205], 0
	v_mfma_f32_16x16x32_bf16 v[26:29], v[138:141], v[202:205], 0
	v_mfma_f32_16x16x32_bf16 v[18:21], v[130:133], v[210:213], 0
	v_mfma_f32_16x16x32_bf16 v[10:13], v[138:141], v[210:213], 0
	v_mfma_f32_16x16x32_bf16 v[62:65], v[134:137], v[190:193], v[62:65]
	v_mfma_f32_16x16x32_bf16 v[58:61], v[142:145], v[190:193], v[58:61]
	v_mfma_f32_16x16x32_bf16 v[50:53], v[134:137], v[198:201], v[50:53]
	v_mfma_f32_16x16x32_bf16 v[42:45], v[142:145], v[198:201], v[42:45]
	v_mfma_f32_16x16x32_bf16 v[34:37], v[134:137], v[206:209], v[34:37]
	v_mfma_f32_16x16x32_bf16 v[26:29], v[142:145], v[206:209], v[26:29]
	v_mfma_f32_16x16x32_bf16 v[18:21], v[134:137], v[214:217], v[18:21]
	v_mfma_f32_16x16x32_bf16 v[10:13], v[142:145], v[214:217], v[10:13]
	v_mfma_f32_16x16x32_bf16 v[54:57], v[170:173], v[186:189], 0
	v_mfma_f32_16x16x32_bf16 v[46:49], v[178:181], v[186:189], 0
	v_mfma_f32_16x16x32_bf16 v[38:41], v[170:173], v[194:197], 0
	v_mfma_f32_16x16x32_bf16 v[30:33], v[178:181], v[194:197], 0
	v_mfma_f32_16x16x32_bf16 v[22:25], v[170:173], v[202:205], 0
	v_mfma_f32_16x16x32_bf16 v[14:17], v[178:181], v[202:205], 0
	v_mfma_f32_16x16x32_bf16 v[6:9], v[170:173], v[210:213], 0
	v_mfma_f32_16x16x32_bf16 v[2:5], v[178:181], v[210:213], 0
	v_mfma_f32_16x16x32_bf16 v[54:57], v[174:177], v[190:193], v[54:57]
	v_mfma_f32_16x16x32_bf16 v[46:49], v[182:185], v[190:193], v[46:49]
	v_mfma_f32_16x16x32_bf16 v[38:41], v[174:177], v[198:201], v[38:41]
	v_mfma_f32_16x16x32_bf16 v[30:33], v[182:185], v[198:201], v[30:33]
	v_mfma_f32_16x16x32_bf16 v[22:25], v[174:177], v[206:209], v[22:25]
	v_mfma_f32_16x16x32_bf16 v[14:17], v[182:185], v[206:209], v[14:17]
	v_mfma_f32_16x16x32_bf16 v[6:9], v[174:177], v[214:217], v[6:9]
	v_mfma_f32_16x16x32_bf16 v[2:5], v[182:185], v[214:217], v[2:5]
	s_barrier
	s_add_i32 s72, 0, 0x18000
	s_add_i32 s73, 0, 0x1c000
	v_add_u32_e32 v142, s72, v164
	v_add_u32_e32 v169, s73, v164
	ds_read_b128 v[130:133], v142
	ds_read_b128 v[134:137], v142 offset:1024
	ds_read_b128 v[138:141], v142 offset:2048
	ds_read_b128 v[142:145], v142 offset:3072
	ds_read_b128 v[170:173], v169
	ds_read_b128 v[174:177], v169 offset:1024
	ds_read_b128 v[178:181], v169 offset:2048
	ds_read_b128 v[182:185], v169 offset:3072
	s_add_u32 s24, s24, 0x100000
	s_addc_u32 s25, s25, 0
	s_mov_b32 m0, s34
	ds_read_b128 v[186:189], v168 offset:32768
	ds_read_b128 v[190:193], v168 offset:33792
	ds_read_b128 v[194:197], v168 offset:34816
	ds_read_b128 v[198:201], v168 offset:35840
	ds_read_b128 v[202:205], v168 offset:36864
	ds_read_b128 v[206:209], v168 offset:37888
	ds_read_b128 v[210:213], v168 offset:38912
	ds_read_b128 v[214:217], v168 offset:39936
	global_load_lds_dwordx4 v152, s[24:25]
	s_mov_b32 m0, s35
	s_nop 0
	global_load_lds_dwordx4 v148, s[24:25]
	s_waitcnt vmcnt(8)
	s_waitcnt lgkmcnt(0)
	s_barrier
	s_waitcnt lgkmcnt(0)
	v_mfma_f32_16x16x32_bf16 v[126:129], v[130:133], v[186:189], v[126:129]
	v_mfma_f32_16x16x32_bf16 v[122:125], v[138:141], v[186:189], v[122:125]
	v_mfma_f32_16x16x32_bf16 v[118:121], v[130:133], v[194:197], v[118:121]
	v_mfma_f32_16x16x32_bf16 v[114:117], v[138:141], v[194:197], v[114:117]
	v_mfma_f32_16x16x32_bf16 v[110:113], v[130:133], v[202:205], v[110:113]
	v_mfma_f32_16x16x32_bf16 v[102:105], v[138:141], v[202:205], v[102:105]
	v_mfma_f32_16x16x32_bf16 v[94:97], v[130:133], v[210:213], v[94:97]
	v_mfma_f32_16x16x32_bf16 v[86:89], v[138:141], v[210:213], v[86:89]
	v_mfma_f32_16x16x32_bf16 v[126:129], v[134:137], v[190:193], v[126:129]
	v_mfma_f32_16x16x32_bf16 v[122:125], v[142:145], v[190:193], v[122:125]
	v_mfma_f32_16x16x32_bf16 v[118:121], v[134:137], v[198:201], v[118:121]
	v_mfma_f32_16x16x32_bf16 v[114:117], v[142:145], v[198:201], v[114:117]
	v_mfma_f32_16x16x32_bf16 v[110:113], v[134:137], v[206:209], v[110:113]
	v_mfma_f32_16x16x32_bf16 v[102:105], v[142:145], v[206:209], v[102:105]
	v_mfma_f32_16x16x32_bf16 v[94:97], v[134:137], v[214:217], v[94:97]
	v_mfma_f32_16x16x32_bf16 v[86:89], v[142:145], v[214:217], v[86:89]
	v_mfma_f32_16x16x32_bf16 v[106:109], v[170:173], v[186:189], v[106:109]
	v_mfma_f32_16x16x32_bf16 v[98:101], v[178:181], v[186:189], v[98:101]
	v_mfma_f32_16x16x32_bf16 v[90:93], v[170:173], v[194:197], v[90:93]
	v_mfma_f32_16x16x32_bf16 v[82:85], v[178:181], v[194:197], v[82:85]
	v_mfma_f32_16x16x32_bf16 v[78:81], v[170:173], v[202:205], v[78:81]
	v_mfma_f32_16x16x32_bf16 v[74:77], v[178:181], v[202:205], v[74:77]
	v_mfma_f32_16x16x32_bf16 v[70:73], v[170:173], v[210:213], v[70:73]
	v_mfma_f32_16x16x32_bf16 v[66:69], v[178:181], v[210:213], v[66:69]
	v_mfma_f32_16x16x32_bf16 v[106:109], v[174:177], v[190:193], v[106:109]
	v_mfma_f32_16x16x32_bf16 v[98:101], v[182:185], v[190:193], v[98:101]
	v_mfma_f32_16x16x32_bf16 v[90:93], v[174:177], v[198:201], v[90:93]
	v_mfma_f32_16x16x32_bf16 v[82:85], v[182:185], v[198:201], v[82:85]
	v_mfma_f32_16x16x32_bf16 v[78:81], v[174:177], v[206:209], v[78:81]
	v_mfma_f32_16x16x32_bf16 v[74:77], v[182:185], v[206:209], v[74:77]
	v_mfma_f32_16x16x32_bf16 v[70:73], v[174:177], v[214:217], v[70:73]
	v_mfma_f32_16x16x32_bf16 v[66:69], v[182:185], v[214:217], v[66:69]
	s_barrier
; #define PG8_STAGE(bufoff, gbase, voff) do { _Pragma("unroll") for (int _i = 0; _i < 2; ++_i) \
;         __builtin_amdgcn_global_load_lds((const unsigned*)((const char*)(gbase) + (voff)[_i]), (PG8_LAS unsigned*)(lds + (bufoff) + ldsw + _i * 8192), 16, 0, 0); } while (0)
; #define PG8_LDA(dst, b, h) do { _Pragma("unroll") for (int m = 0; m < 4; ++m) _Pragma("unroll") for (int k = 0; k < 2; ++k) dst[m][k] = *(const PG8_LAS bf16x8*)(lds + PG8_SA(b, h) + aoff + m * 2048 + k * 1024); } while (0)
; #define PG8_MMA(ai, bj, At, Bt) do { __builtin_amdgcn_s_setprio(1); _Pragma("unroll") for (int m = 0; m < 4; ++m) _Pragma("unroll") for (int n = 0; n < 2; ++n) _Pragma("unroll") for (int k = 0; k < 2; ++k) \
;         acc[ai][bj][m][n] = __builtin_amdgcn_mfma_f32_16x16x32_bf16(Bt[n][k], At[m][k], acc[ai][bj][m][n], 0, 0, 0); __builtin_amdgcn_s_setprio(0); } while (0)
; #define PG8_WAIT_V(n) asm volatile("s_waitcnt vmcnt(" #n ")" ::: "memory")
; #define PG8_WAIT_L(n) asm volatile("s_waitcnt lgkmcnt(" #n ")" ::: "memory")
; #define PG8_BAR __builtin_amdgcn_s_barrier()
; #define PG8_SCHED __builtin_amdgcn_sched_barrier(0)
; template <class Epi, class Sched, bool ALIGN_EPI = false, bool SP2 = false>
; __device__ __forceinline__ void gemm_phase(PG8_LAS unsigned char* lds, const Gemm g, const Sched& S, const Epi& E) {
;     ...
;             PG8_LDA(At, 1, 1); PG8_STAGE(PG8_SB(1, 0), b3, voffB); PG8_STAGE(PG8_SB(1, 1), b3 + hstepB, voffB); PG8_STAGE(PG8_SA(1, 0), a3, voffA);
;             PG8_WAIT_V(8); PG8_WAIT_L(0); PG8_BAR; PG8_MMA(1, 0, At, B0); PG8_MMA(1, 1, At, B1); PG8_BAR; PG8_SCHED;
	s_add_i32 s24, s72, s26
	s_mov_b32 m0, s24
	ds_read_b128 v[186:189], v168 offset:49152
	ds_read_b128 v[190:193], v168 offset:50176
	ds_read_b128 v[194:197], v168 offset:51200
	ds_read_b128 v[198:201], v168 offset:52224
	ds_read_b128 v[202:205], v168 offset:53248
	ds_read_b128 v[206:209], v168 offset:54272
	ds_read_b128 v[210:213], v168 offset:55296
	ds_read_b128 v[214:217], v168 offset:56320
	global_load_lds_dwordx4 v150, s[98:99]
	s_add_i32 m0, s24, 0x2000
	s_add_u32 s24, s38, 0x100080
	s_addc_u32 s25, s39, 0
	s_add_i32 s38, s73, s26
	global_load_lds_dwordx4 v146, s[98:99]
	s_mov_b32 m0, s38
	s_nop 0
	global_load_lds_dwordx4 v150, s[24:25]
	s_add_i32 m0, s38, 0x2000
	s_nop 0
	global_load_lds_dwordx4 v146, s[24:25]
	s_mov_b32 m0, s43
	s_nop 0
	global_load_lds_dwordx4 v152, s[100:101]
	s_mov_b32 m0, s44
	s_nop 0
	global_load_lds_dwordx4 v148, s[100:101]
	s_waitcnt vmcnt(8)
	s_waitcnt lgkmcnt(0)
	s_barrier
	s_waitcnt lgkmcnt(0)
	v_mfma_f32_16x16x32_bf16 v[62:65], v[130:133], v[186:189], v[62:65]
	v_mfma_f32_16x16x32_bf16 v[58:61], v[138:141], v[186:189], v[58:61]
	v_mfma_f32_16x16x32_bf16 v[50:53], v[130:133], v[194:197], v[50:53]
	v_mfma_f32_16x16x32_bf16 v[42:45], v[138:141], v[194:197], v[42:45]
	v_mfma_f32_16x16x32_bf16 v[34:37], v[130:133], v[202:205], v[34:37]
	v_mfma_f32_16x16x32_bf16 v[26:29], v[138:141], v[202:205], v[26:29]
	v_mfma_f32_16x16x32_bf16 v[18:21], v[130:133], v[210:213], v[18:21]
	v_mfma_f32_16x16x32_bf16 v[10:13], v[138:141], v[210:213], v[10:13]
	v_mfma_f32_16x16x32_bf16 v[62:65], v[134:137], v[190:193], v[62:65]
	v_mfma_f32_16x16x32_bf16 v[58:61], v[142:145], v[190:193], v[58:61]
	v_mfma_f32_16x16x32_bf16 v[50:53], v[134:137], v[198:201], v[50:53]
	v_mfma_f32_16x16x32_bf16 v[42:45], v[142:145], v[198:201], v[42:45]
	v_mfma_f32_16x16x32_bf16 v[34:37], v[134:137], v[206:209], v[34:37]
	v_mfma_f32_16x16x32_bf16 v[26:29], v[142:145], v[206:209], v[26:29]
	v_mfma_f32_16x16x32_bf16 v[18:21], v[134:137], v[214:217], v[18:21]
	v_mfma_f32_16x16x32_bf16 v[10:13], v[142:145], v[214:217], v[10:13]
	v_mfma_f32_16x16x32_bf16 v[54:57], v[170:173], v[186:189], v[54:57]
	v_mfma_f32_16x16x32_bf16 v[46:49], v[178:181], v[186:189], v[46:49]
	v_mfma_f32_16x16x32_bf16 v[38:41], v[170:173], v[194:197], v[38:41]
	v_mfma_f32_16x16x32_bf16 v[30:33], v[178:181], v[194:197], v[30:33]
	v_mfma_f32_16x16x32_bf16 v[22:25], v[170:173], v[202:205], v[22:25]
	v_mfma_f32_16x16x32_bf16 v[14:17], v[178:181], v[202:205], v[14:17]
	v_mfma_f32_16x16x32_bf16 v[6:9], v[170:173], v[210:213], v[6:9]
	v_mfma_f32_16x16x32_bf16 v[2:5], v[178:181], v[210:213], v[2:5]
	v_mfma_f32_16x16x32_bf16 v[54:57], v[174:177], v[190:193], v[54:57]
	v_mfma_f32_16x16x32_bf16 v[46:49], v[182:185], v[190:193], v[46:49]
	v_mfma_f32_16x16x32_bf16 v[38:41], v[174:177], v[198:201], v[38:41]
	v_mfma_f32_16x16x32_bf16 v[30:33], v[182:185], v[198:201], v[30:33]
	v_mfma_f32_16x16x32_bf16 v[22:25], v[174:177], v[206:209], v[22:25]
	v_mfma_f32_16x16x32_bf16 v[14:17], v[182:185], v[206:209], v[14:17]
	v_mfma_f32_16x16x32_bf16 v[6:9], v[174:177], v[214:217], v[6:9]
	v_mfma_f32_16x16x32_bf16 v[2:5], v[182:185], v[214:217], v[2:5]
	s_barrier
	s_add_i32 s69, s69, 2
	s_add_u32 s36, s36, 0x100
	s_addc_u32 s37, s37, 0
	s_add_u32 s63, s63, 0x100
	s_addc_u32 s68, s68, 0
	s_cmp_gt_u32 s69, 61

; #define PG8_STAGE(bufoff, gbase, voff) do { _Pragma("unroll") for (int _i = 0; _i < 2; ++_i) \
;         __builtin_amdgcn_global_load_lds((const unsigned*)((const char*)(gbase) + (voff)[_i]), (PG8_LAS unsigned*)(lds + (bufoff) + ldsw + _i * 8192), 16, 0, 0); } while (0)
; #define PG8_LDA(dst, b, h) do { _Pragma("unroll") for (int m = 0; m < 4; ++m) _Pragma("unroll") for (int k = 0; k < 2; ++k) dst[m][k] = *(const PG8_LAS bf16x8*)(lds + PG8_SA(b, h) + aoff + m * 2048 + k * 1024); } while (0)
; #define PG8_LDB(dst, b, h) do { _Pragma("unroll") for (int n = 0; n < 2; ++n) _Pragma("unroll") for (int k = 0; k < 2; ++k) dst[n][k] = *(const PG8_LAS bf16x8*)(lds + PG8_SB(b, h) + boff + n * 2048 + k * 1024); } while (0)
; #define PG8_MMA(ai, bj, At, Bt) do { __builtin_amdgcn_s_setprio(1); _Pragma("unroll") for (int m = 0; m < 4; ++m) _Pragma("unroll") for (int n = 0; n < 2; ++n) _Pragma("unroll") for (int k = 0; k < 2; ++k) \
;         acc[ai][bj][m][n] = __builtin_amdgcn_mfma_f32_16x16x32_bf16(Bt[n][k], At[m][k], acc[ai][bj][m][n], 0, 0, 0); __builtin_amdgcn_s_setprio(0); } while (0)
; template <class Epi, class Sched, bool ALIGN_EPI = false, bool SP2 = false>
; __device__ __forceinline__ void gemm_phase(PG8_LAS unsigned char* lds, const Gemm g, const Sched& S, const Epi& E) {
;     ...
;         const char* nA = has_next ? (const char*)g.A + (size_t)nxt.pm * tstepA + (size_t)((nxt.pn >> g.a_shift) * g.a_stride) : cA; const char* nB = has_next ? (const char*)g.Bt + (size_t)nxt.pn * tstepB : cB;
; #pragma clang loop unroll(disable)
;         for (int t = 0; t < nt; t += 2) {
;             const bool last = (t == nt - 2);
;             const char* a1 = cA + (size_t)(t + 1) * kstep;
;             const char* a2 = last ? nA : cA + (size_t)(t + 2) * kstep; const char* b2 = last ? nB : cB + (size_t)(t + 2) * kstep;
;             const char* a3 = a2 + kstep; const char* b3 = b2 + kstep;
;             if (last && has_next) S.a_ready(nxt);
;             if constexpr (SP2) {
;             PG8_LDB(B0, 0, 0); PG8_LDB(B1, 0, 1); PG8_SCHED; PG8_LDA(At, 0, 0); PG8_STAGE(PG8_SA(1, 1), a1 + hstepA, voffA);
;             PG8_WAIT_V(8); PG8_WAIT_L(0); PG8_BAR; PG8_MMA(0, 0, At, B0); PG8_MMA(0, 1, At, B1); PG8_BAR; PG8_SCHED;
;             PG8_LDA(At, 0, 1); PG8_STAGE(PG8_SB(0, 0), b2, voffB); PG8_STAGE(PG8_SB(0, 1), b2 + hstepB, voffB); PG8_STAGE(PG8_SA(0, 0), a2, voffA);
.LBB0_989:
	s_ashr_i32 s23, s22, 31
	s_lshl_b64 s[24:25], s[22:23], 21
	s_add_u32 s24, s92, s24
	s_addc_u32 s25, s93, s25
	s_and_b64 s[34:35], s[6:7], exec
	s_cselect_b32 s23, s25, s41
	s_cselect_b32 s27, s24, s40
	s_ashr_i32 s21, s20, 31
	s_lshl_b64 s[34:35], s[20:21], 21
	s_add_u32 s36, s54, s34
	s_addc_u32 s37, s55, s35
	s_and_b64 s[34:35], s[6:7], exec
	s_cselect_b32 s21, s37, s43
	s_cselect_b32 s39, s36, s42
	s_add_u32 s40, s40, 0x100080
	s_addc_u32 s41, s41, 0
	s_add_u32 s72, s42, 0x100
	s_addc_u32 s73, s43, 0
	s_mov_b32 s74, -2
	s_setprio 1
	s_cmp_eq_u64 s[12:13], 0
	s_cbranch_scc1 .Lsp_LBB0_990
	s_setprio 0
.Lsp_LBB0_990:
	ds_read_b128 v[146:149], v154
	ds_read_b128 v[158:161], v154 offset:1024
	ds_read_b128 v[162:165], v154 offset:2048
	ds_read_b128 v[166:169], v154 offset:3072
	ds_read_b128 v[170:173], v155
	ds_read_b128 v[174:177], v155 offset:1024
	ds_read_b128 v[178:181], v155 offset:2048
	ds_read_b128 v[182:185], v155 offset:3072
	s_add_u32 s34, s40, 0xfff00080
	s_addc_u32 s35, s41, -1
	s_cmp_eq_u32 s74, 60
	s_cselect_b32 s35, s23, s35
	s_cselect_b32 s34, s27, s34
	s_cselect_b32 s43, s21, s73
	s_cselect_b32 s42, s39, s72
	s_add_i32 m0, s45, 0xc000
	ds_read_b128 v[186:189], v156
	ds_read_b128 v[190:193], v156 offset:1024
	ds_read_b128 v[194:197], v156 offset:2048
	ds_read_b128 v[198:201], v156 offset:3072
	ds_read_b128 v[202:205], v156 offset:4096
	ds_read_b128 v[206:209], v156 offset:5120
	ds_read_b128 v[210:213], v156 offset:6144
	ds_read_b128 v[214:217], v156 offset:7168
	global_load_lds_dwordx4 v138, s[40:41]
	s_add_i32 m0, s45, 0xe000
	s_nop 0
	global_load_lds_dwordx4 v140, s[40:41]
	s_waitcnt vmcnt(8)
	s_waitcnt lgkmcnt(0)
	s_barrier
	s_waitcnt lgkmcnt(0)
	v_mfma_f32_16x16x32_bf16 v[126:129], v[146:149], v[186:189], 0
	v_mfma_f32_16x16x32_bf16 v[122:125], v[162:165], v[186:189], 0
	v_mfma_f32_16x16x32_bf16 v[118:121], v[146:149], v[194:197], 0
	v_mfma_f32_16x16x32_bf16 v[114:117], v[162:165], v[194:197], 0
	v_mfma_f32_16x16x32_bf16 v[110:113], v[146:149], v[202:205], 0
	v_mfma_f32_16x16x32_bf16 v[106:109], v[162:165], v[202:205], 0
	v_mfma_f32_16x16x32_bf16 v[102:105], v[146:149], v[210:213], 0
	v_mfma_f32_16x16x32_bf16 v[98:101], v[162:165], v[210:213], 0
	v_mfma_f32_16x16x32_bf16 v[126:129], v[158:161], v[190:193], v[126:129]
	v_mfma_f32_16x16x32_bf16 v[122:125], v[166:169], v[190:193], v[122:125]
	v_mfma_f32_16x16x32_bf16 v[118:121], v[158:161], v[198:201], v[118:121]
	v_mfma_f32_16x16x32_bf16 v[114:117], v[166:169], v[198:201], v[114:117]
	v_mfma_f32_16x16x32_bf16 v[110:113], v[158:161], v[206:209], v[110:113]
	v_mfma_f32_16x16x32_bf16 v[106:109], v[166:169], v[206:209], v[106:109]
	v_mfma_f32_16x16x32_bf16 v[102:105], v[158:161], v[214:217], v[102:105]
	v_mfma_f32_16x16x32_bf16 v[98:101], v[166:169], v[214:217], v[98:101]
	v_mfma_f32_16x16x32_bf16 v[62:65], v[170:173], v[186:189], 0
	v_mfma_f32_16x16x32_bf16 v[58:61], v[178:181], v[186:189], 0
	v_mfma_f32_16x16x32_bf16 v[54:57], v[170:173], v[194:197], 0
	v_mfma_f32_16x16x32_bf16 v[50:53], v[178:181], v[194:197], 0
	v_mfma_f32_16x16x32_bf16 v[46:49], v[170:173], v[202:205], 0
	v_mfma_f32_16x16x32_bf16 v[42:45], v[178:181], v[202:205], 0
	v_mfma_f32_16x16x32_bf16 v[38:41], v[170:173], v[210:213], 0
	v_mfma_f32_16x16x32_bf16 v[34:37], v[178:181], v[210:213], 0
	v_mfma_f32_16x16x32_bf16 v[62:65], v[174:177], v[190:193], v[62:65]
	v_mfma_f32_16x16x32_bf16 v[58:61], v[182:185], v[190:193], v[58:61]
	v_mfma_f32_16x16x32_bf16 v[54:57], v[174:177], v[198:201], v[54:57]
	v_mfma_f32_16x16x32_bf16 v[50:53], v[182:185], v[198:201], v[50:53]
	v_mfma_f32_16x16x32_bf16 v[46:49], v[174:177], v[206:209], v[46:49]
	v_mfma_f32_16x16x32_bf16 v[42:45], v[182:185], v[206:209], v[42:45]
	v_mfma_f32_16x16x32_bf16 v[38:41], v[174:177], v[214:217], v[38:41]
	v_mfma_f32_16x16x32_bf16 v[34:37], v[182:185], v[214:217], v[34:37]
	s_barrier
	s_add_i32 s75, s64, s17
	s_add_u32 s98, s42, 0x80
	s_addc_u32 s99, s43, 0
	s_add_u32 s100, s34, 0x80
	s_addc_u32 s101, s35, 0
	s_mov_b32 m0, s75
	ds_read_b128 v[186:189], v156 offset:16384
	ds_read_b128 v[190:193], v156 offset:17408
	ds_read_b128 v[194:197], v156 offset:18432
	ds_read_b128 v[198:201], v156 offset:19456
	ds_read_b128 v[202:205], v156 offset:20480
	ds_read_b128 v[206:209], v156 offset:21504
	ds_read_b128 v[210:213], v156 offset:22528
	ds_read_b128 v[214:217], v156 offset:23552
	global_load_lds_dwordx4 v134, s[42:43]
	s_add_i32 m0, s75, 0x2000
	s_add_u32 s76, s42, 0x100000
	s_addc_u32 s77, s43, 0
	s_add_i32 s75, s65, s17
	global_load_lds_dwordx4 v130, s[42:43]
	s_mov_b32 m0, s75
	s_nop 0
	global_load_lds_dwordx4 v134, s[76:77]
	s_add_i32 m0, s75, 0x2000
	s_nop 0
	global_load_lds_dwordx4 v130, s[76:77]
	s_mov_b32 m0, s45
	s_nop 0
	global_load_lds_dwordx4 v136, s[34:35]
	s_mov_b32 m0, s46
	s_nop 0
	global_load_lds_dwordx4 v132, s[34:35]
	s_waitcnt vmcnt(8)
	s_waitcnt lgkmcnt(0)
	s_barrier
; #define PG8_STAGE(bufoff, gbase, voff) do { _Pragma("unroll") for (int _i = 0; _i < 2; ++_i) \
;         __builtin_amdgcn_global_load_lds((const unsigned*)((const char*)(gbase) + (voff)[_i]), (PG8_LAS unsigned*)(lds + (bufoff) + ldsw + _i * 8192), 16, 0, 0); } while (0)
; #define PG8_LDA(dst, b, h) do { _Pragma("unroll") for (int m = 0; m < 4; ++m) _Pragma("unroll") for (int k = 0; k < 2; ++k) dst[m][k] = *(const PG8_LAS bf16x8*)(lds + PG8_SA(b, h) + aoff + m * 2048 + k * 1024); } while (0)
; #define PG8_LDB(dst, b, h) do { _Pragma("unroll") for (int n = 0; n < 2; ++n) _Pragma("unroll") for (int k = 0; k < 2; ++k) dst[n][k] = *(const PG8_LAS bf16x8*)(lds + PG8_SB(b, h) + boff + n * 2048 + k * 1024); } while (0)
; #define PG8_MMA(ai, bj, At, Bt) do { __builtin_amdgcn_s_setprio(1); _Pragma("unroll") for (int m = 0; m < 4; ++m) _Pragma("unroll") for (int n = 0; n < 2; ++n) _Pragma("unroll") for (int k = 0; k < 2; ++k) \
;         acc[ai][bj][m][n] = __builtin_amdgcn_mfma_f32_16x16x32_bf16(Bt[n][k], At[m][k], acc[ai][bj][m][n], 0, 0, 0); __builtin_amdgcn_s_setprio(0); } while (0)
; #define PG8_WAIT_V(n) asm volatile("s_waitcnt vmcnt(" #n ")" ::: "memory")
; #define PG8_WAIT_L(n) asm volatile("s_waitcnt lgkmcnt(" #n ")" ::: "memory")
; #define PG8_BAR __builtin_amdgcn_s_barrier()
; #define PG8_SCHED __builtin_amdgcn_sched_barrier(0)
; template <class Epi, class Sched, bool ALIGN_EPI = false, bool SP2 = false>
; __device__ __forceinline__ void gemm_phase(PG8_LAS unsigned char* lds, const Gemm g, const Sched& S, const Epi& E) {
;     ...
;             PG8_LDA(At, 0, 1); PG8_STAGE(PG8_SB(0, 0), b2, voffB); PG8_STAGE(PG8_SB(0, 1), b2 + hstepB, voffB); PG8_STAGE(PG8_SA(0, 0), a2, voffA);
;             PG8_WAIT_V(8); PG8_WAIT_L(0); PG8_BAR; PG8_MMA(1, 0, At, B0); PG8_MMA(1, 1, At, B1); PG8_BAR; PG8_SCHED;
;             PG8_LDB(B0, 1, 0); PG8_LDB(B1, 1, 1); PG8_SCHED; PG8_LDA(At, 1, 0); PG8_STAGE(PG8_SA(0, 1), a2 + hstepA, voffA);
;             PG8_WAIT_V(8); PG8_WAIT_L(0); PG8_BAR; PG8_MMA(0, 0, At, B0); PG8_MMA(0, 1, At, B1); PG8_BAR; PG8_SCHED;
;             PG8_LDA(At, 1, 1); PG8_STAGE(PG8_SB(1, 0), b3, voffB); PG8_STAGE(PG8_SB(1, 1), b3 + hstepB, voffB); PG8_STAGE(PG8_SA(1, 0), a3, voffA);
	s_waitcnt lgkmcnt(0)
	v_mfma_f32_16x16x32_bf16 v[94:97], v[146:149], v[186:189], 0
	v_mfma_f32_16x16x32_bf16 v[90:93], v[162:165], v[186:189], 0
	v_mfma_f32_16x16x32_bf16 v[86:89], v[146:149], v[194:197], 0
	v_mfma_f32_16x16x32_bf16 v[82:85], v[162:165], v[194:197], 0
	v_mfma_f32_16x16x32_bf16 v[78:81], v[146:149], v[202:205], 0
	v_mfma_f32_16x16x32_bf16 v[74:77], v[162:165], v[202:205], 0
	v_mfma_f32_16x16x32_bf16 v[70:73], v[146:149], v[210:213], 0
	v_mfma_f32_16x16x32_bf16 v[66:69], v[162:165], v[210:213], 0
	v_mfma_f32_16x16x32_bf16 v[94:97], v[158:161], v[190:193], v[94:97]
	v_mfma_f32_16x16x32_bf16 v[90:93], v[166:169], v[190:193], v[90:93]
	v_mfma_f32_16x16x32_bf16 v[86:89], v[158:161], v[198:201], v[86:89]
	v_mfma_f32_16x16x32_bf16 v[82:85], v[166:169], v[198:201], v[82:85]
	v_mfma_f32_16x16x32_bf16 v[78:81], v[158:161], v[206:209], v[78:81]
	v_mfma_f32_16x16x32_bf16 v[74:77], v[166:169], v[206:209], v[74:77]
	v_mfma_f32_16x16x32_bf16 v[70:73], v[158:161], v[214:217], v[70:73]
	v_mfma_f32_16x16x32_bf16 v[66:69], v[166:169], v[214:217], v[66:69]
	v_mfma_f32_16x16x32_bf16 v[30:33], v[170:173], v[186:189], 0
	v_mfma_f32_16x16x32_bf16 v[26:29], v[178:181], v[186:189], 0
	v_mfma_f32_16x16x32_bf16 v[22:25], v[170:173], v[194:197], 0
	v_mfma_f32_16x16x32_bf16 v[18:21], v[178:181], v[194:197], 0
	v_mfma_f32_16x16x32_bf16 v[14:17], v[170:173], v[202:205], 0
	v_mfma_f32_16x16x32_bf16 v[10:13], v[178:181], v[202:205], 0
	v_mfma_f32_16x16x32_bf16 v[6:9], v[170:173], v[210:213], 0
	v_mfma_f32_16x16x32_bf16 v[2:5], v[178:181], v[210:213], 0
	v_mfma_f32_16x16x32_bf16 v[30:33], v[174:177], v[190:193], v[30:33]
	v_mfma_f32_16x16x32_bf16 v[26:29], v[182:185], v[190:193], v[26:29]
	v_mfma_f32_16x16x32_bf16 v[22:25], v[174:177], v[198:201], v[22:25]
	v_mfma_f32_16x16x32_bf16 v[18:21], v[182:185], v[198:201], v[18:21]
	v_mfma_f32_16x16x32_bf16 v[14:17], v[174:177], v[206:209], v[14:17]
	v_mfma_f32_16x16x32_bf16 v[10:13], v[182:185], v[206:209], v[10:13]
	v_mfma_f32_16x16x32_bf16 v[6:9], v[174:177], v[214:217], v[6:9]
	v_mfma_f32_16x16x32_bf16 v[2:5], v[182:185], v[214:217], v[2:5]
	s_barrier
	s_add_i32 s75, 0, 0x18000
	v_add_u32_e32 v157, s75, v152
	s_add_i32 s76, 0, 0x1c000
	ds_read_b128 v[146:149], v157
	ds_read_b128 v[158:161], v157 offset:1024
	ds_read_b128 v[162:165], v157 offset:2048
	ds_read_b128 v[166:169], v157 offset:3072
	v_add_u32_e32 v157, s76, v152
	ds_read_b128 v[170:173], v157
	ds_read_b128 v[174:177], v157 offset:1024
	ds_read_b128 v[178:181], v157 offset:2048
	ds_read_b128 v[182:185], v157 offset:3072
	s_add_u32 s34, s34, 0x100000
	s_addc_u32 s35, s35, 0
	s_mov_b32 m0, s47
	ds_read_b128 v[186:189], v156 offset:32768
	ds_read_b128 v[190:193], v156 offset:33792
	ds_read_b128 v[194:197], v156 offset:34816
	ds_read_b128 v[198:201], v156 offset:35840
	ds_read_b128 v[202:205], v156 offset:36864
	ds_read_b128 v[206:209], v156 offset:37888
	ds_read_b128 v[210:213], v156 offset:38912
	ds_read_b128 v[214:217], v156 offset:39936
	global_load_lds_dwordx4 v136, s[34:35]
	s_mov_b32 m0, s48
	s_nop 0
	global_load_lds_dwordx4 v132, s[34:35]
	s_waitcnt vmcnt(8)
	s_waitcnt lgkmcnt(0)
	s_barrier
	s_waitcnt lgkmcnt(0)
	v_mfma_f32_16x16x32_bf16 v[126:129], v[146:149], v[186:189], v[126:129]
	v_mfma_f32_16x16x32_bf16 v[122:125], v[162:165], v[186:189], v[122:125]
	v_mfma_f32_16x16x32_bf16 v[118:121], v[146:149], v[194:197], v[118:121]
	v_mfma_f32_16x16x32_bf16 v[114:117], v[162:165], v[194:197], v[114:117]
	v_mfma_f32_16x16x32_bf16 v[110:113], v[146:149], v[202:205], v[110:113]
	v_mfma_f32_16x16x32_bf16 v[106:109], v[162:165], v[202:205], v[106:109]
	v_mfma_f32_16x16x32_bf16 v[102:105], v[146:149], v[210:213], v[102:105]
	v_mfma_f32_16x16x32_bf16 v[98:101], v[162:165], v[210:213], v[98:101]
	v_mfma_f32_16x16x32_bf16 v[126:129], v[158:161], v[190:193], v[126:129]
	v_mfma_f32_16x16x32_bf16 v[122:125], v[166:169], v[190:193], v[122:125]
	v_mfma_f32_16x16x32_bf16 v[118:121], v[158:161], v[198:201], v[118:121]
	v_mfma_f32_16x16x32_bf16 v[114:117], v[166:169], v[198:201], v[114:117]
	v_mfma_f32_16x16x32_bf16 v[110:113], v[158:161], v[206:209], v[110:113]
	v_mfma_f32_16x16x32_bf16 v[106:109], v[166:169], v[206:209], v[106:109]
	v_mfma_f32_16x16x32_bf16 v[102:105], v[158:161], v[214:217], v[102:105]
	v_mfma_f32_16x16x32_bf16 v[98:101], v[166:169], v[214:217], v[98:101]
	v_mfma_f32_16x16x32_bf16 v[62:65], v[170:173], v[186:189], v[62:65]
	v_mfma_f32_16x16x32_bf16 v[58:61], v[178:181], v[186:189], v[58:61]
	v_mfma_f32_16x16x32_bf16 v[54:57], v[170:173], v[194:197], v[54:57]
	v_mfma_f32_16x16x32_bf16 v[50:53], v[178:181], v[194:197], v[50:53]
	v_mfma_f32_16x16x32_bf16 v[46:49], v[170:173], v[202:205], v[46:49]
	v_mfma_f32_16x16x32_bf16 v[42:45], v[178:181], v[202:205], v[42:45]
	v_mfma_f32_16x16x32_bf16 v[38:41], v[170:173], v[210:213], v[38:41]
	v_mfma_f32_16x16x32_bf16 v[34:37], v[178:181], v[210:213], v[34:37]
	v_mfma_f32_16x16x32_bf16 v[62:65], v[174:177], v[190:193], v[62:65]
	v_mfma_f32_16x16x32_bf16 v[58:61], v[182:185], v[190:193], v[58:61]
	v_mfma_f32_16x16x32_bf16 v[54:57], v[174:177], v[198:201], v[54:57]
	v_mfma_f32_16x16x32_bf16 v[50:53], v[182:185], v[198:201], v[50:53]
	v_mfma_f32_16x16x32_bf16 v[46:49], v[174:177], v[206:209], v[46:49]
	v_mfma_f32_16x16x32_bf16 v[42:45], v[182:185], v[206:209], v[42:45]
	v_mfma_f32_16x16x32_bf16 v[38:41], v[174:177], v[214:217], v[38:41]
	v_mfma_f32_16x16x32_bf16 v[34:37], v[182:185], v[214:217], v[34:37]
	s_barrier
; #define PG8_STAGE(bufoff, gbase, voff) do { _Pragma("unroll") for (int _i = 0; _i < 2; ++_i) \
;         __builtin_amdgcn_global_load_lds((const unsigned*)((const char*)(gbase) + (voff)[_i]), (PG8_LAS unsigned*)(lds + (bufoff) + ldsw + _i * 8192), 16, 0, 0); } while (0)
; #define PG8_LDA(dst, b, h) do { _Pragma("unroll") for (int m = 0; m < 4; ++m) _Pragma("unroll") for (int k = 0; k < 2; ++k) dst[m][k] = *(const PG8_LAS bf16x8*)(lds + PG8_SA(b, h) + aoff + m * 2048 + k * 1024); } while (0)
; #define PG8_MMA(ai, bj, At, Bt) do { __builtin_amdgcn_s_setprio(1); _Pragma("unroll") for (int m = 0; m < 4; ++m) _Pragma("unroll") for (int n = 0; n < 2; ++n) _Pragma("unroll") for (int k = 0; k < 2; ++k) \
;         acc[ai][bj][m][n] = __builtin_amdgcn_mfma_f32_16x16x32_bf16(Bt[n][k], At[m][k], acc[ai][bj][m][n], 0, 0, 0); __builtin_amdgcn_s_setprio(0); } while (0)
; #define PG8_WAIT_V(n) asm volatile("s_waitcnt vmcnt(" #n ")" ::: "memory")
; #define PG8_WAIT_L(n) asm volatile("s_waitcnt lgkmcnt(" #n ")" ::: "memory")
; #define PG8_BAR __builtin_amdgcn_s_barrier()
; #define PG8_SCHED __builtin_amdgcn_sched_barrier(0)
; template <class Epi, class Sched, bool ALIGN_EPI = false, bool SP2 = false>
; __device__ __forceinline__ void gemm_phase(PG8_LAS unsigned char* lds, const Gemm g, const Sched& S, const Epi& E) {
;     ...
;             PG8_LDA(At, 1, 1); PG8_STAGE(PG8_SB(1, 0), b3, voffB); PG8_STAGE(PG8_SB(1, 1), b3 + hstepB, voffB); PG8_STAGE(PG8_SA(1, 0), a3, voffA);
;             PG8_WAIT_V(8); PG8_WAIT_L(0); PG8_BAR; PG8_MMA(1, 0, At, B0); PG8_MMA(1, 1, At, B1); PG8_BAR; PG8_SCHED;
	s_add_i32 s34, s75, s17
	s_mov_b32 m0, s34
	ds_read_b128 v[186:189], v156 offset:49152
	ds_read_b128 v[190:193], v156 offset:50176
	ds_read_b128 v[194:197], v156 offset:51200
	ds_read_b128 v[198:201], v156 offset:52224
	ds_read_b128 v[202:205], v156 offset:53248
	ds_read_b128 v[206:209], v156 offset:54272
	ds_read_b128 v[210:213], v156 offset:55296
	ds_read_b128 v[214:217], v156 offset:56320
	global_load_lds_dwordx4 v134, s[98:99]
	s_add_i32 m0, s34, 0x2000
	s_add_u32 s34, s42, 0x100080
	s_addc_u32 s35, s43, 0
	s_add_i32 s42, s76, s17
	global_load_lds_dwordx4 v130, s[98:99]
	s_mov_b32 m0, s42
	s_nop 0
	global_load_lds_dwordx4 v134, s[34:35]
	s_add_i32 m0, s42, 0x2000
	s_nop 0
	global_load_lds_dwordx4 v130, s[34:35]
	s_mov_b32 m0, s52
	s_nop 0
	global_load_lds_dwordx4 v136, s[100:101]
	s_mov_b32 m0, s53
	s_nop 0
	global_load_lds_dwordx4 v132, s[100:101]
	s_waitcnt vmcnt(8)
	s_waitcnt lgkmcnt(0)
	s_barrier
	s_waitcnt lgkmcnt(0)
	v_mfma_f32_16x16x32_bf16 v[94:97], v[146:149], v[186:189], v[94:97]
	v_mfma_f32_16x16x32_bf16 v[90:93], v[162:165], v[186:189], v[90:93]
	v_mfma_f32_16x16x32_bf16 v[86:89], v[146:149], v[194:197], v[86:89]
	v_mfma_f32_16x16x32_bf16 v[82:85], v[162:165], v[194:197], v[82:85]
	v_mfma_f32_16x16x32_bf16 v[78:81], v[146:149], v[202:205], v[78:81]
	v_mfma_f32_16x16x32_bf16 v[74:77], v[162:165], v[202:205], v[74:77]
	v_mfma_f32_16x16x32_bf16 v[70:73], v[146:149], v[210:213], v[70:73]
	v_mfma_f32_16x16x32_bf16 v[66:69], v[162:165], v[210:213], v[66:69]
	v_mfma_f32_16x16x32_bf16 v[94:97], v[158:161], v[190:193], v[94:97]
	v_mfma_f32_16x16x32_bf16 v[90:93], v[166:169], v[190:193], v[90:93]
	v_mfma_f32_16x16x32_bf16 v[86:89], v[158:161], v[198:201], v[86:89]
	v_mfma_f32_16x16x32_bf16 v[82:85], v[166:169], v[198:201], v[82:85]
	v_mfma_f32_16x16x32_bf16 v[78:81], v[158:161], v[206:209], v[78:81]
	v_mfma_f32_16x16x32_bf16 v[74:77], v[166:169], v[206:209], v[74:77]
	v_mfma_f32_16x16x32_bf16 v[70:73], v[158:161], v[214:217], v[70:73]
	v_mfma_f32_16x16x32_bf16 v[66:69], v[166:169], v[214:217], v[66:69]
	v_mfma_f32_16x16x32_bf16 v[30:33], v[170:173], v[186:189], v[30:33]
	v_mfma_f32_16x16x32_bf16 v[26:29], v[178:181], v[186:189], v[26:29]
	v_mfma_f32_16x16x32_bf16 v[22:25], v[170:173], v[194:197], v[22:25]
	v_mfma_f32_16x16x32_bf16 v[18:21], v[178:181], v[194:197], v[18:21]
	v_mfma_f32_16x16x32_bf16 v[14:17], v[170:173], v[202:205], v[14:17]
	v_mfma_f32_16x16x32_bf16 v[10:13], v[178:181], v[202:205], v[10:13]
	v_mfma_f32_16x16x32_bf16 v[6:9], v[170:173], v[210:213], v[6:9]
	v_mfma_f32_16x16x32_bf16 v[2:5], v[178:181], v[210:213], v[2:5]
	v_mfma_f32_16x16x32_bf16 v[30:33], v[174:177], v[190:193], v[30:33]
	v_mfma_f32_16x16x32_bf16 v[26:29], v[182:185], v[190:193], v[26:29]
	v_mfma_f32_16x16x32_bf16 v[22:25], v[174:177], v[198:201], v[22:25]
	v_mfma_f32_16x16x32_bf16 v[18:21], v[182:185], v[198:201], v[18:21]
	v_mfma_f32_16x16x32_bf16 v[14:17], v[174:177], v[206:209], v[14:17]
	v_mfma_f32_16x16x32_bf16 v[10:13], v[182:185], v[206:209], v[10:13]
	v_mfma_f32_16x16x32_bf16 v[6:9], v[174:177], v[214:217], v[6:9]
	v_mfma_f32_16x16x32_bf16 v[2:5], v[182:185], v[214:217], v[2:5]
	s_barrier
	s_add_i32 s74, s74, 2
	s_add_u32 s40, s40, 0x100
	s_addc_u32 s41, s41, 0
	s_add_u32 s72, s72, 0x100
	s_addc_u32 s73, s73, 0
	s_cmp_gt_u32 s74, 61

; template <class Epi, class Sched, bool ALIGN_EPI = false, bool SP2 = false>
; __device__ __forceinline__ void gemm_phase(PG8_LAS unsigned char* lds, const Gemm g, const Sched& S, const Epi& E) {
;     ...
;         const char* nA = has_next ? (const char*)g.A + (size_t)nxt.pm * tstepA + (size_t)((nxt.pn >> g.a_shift) * g.a_stride) : cA; const char* nB = has_next ? (const char*)g.Bt + (size_t)nxt.pn * tstepB : cB;
; #pragma clang loop unroll(disable)
;         for (int t = 0; t < nt; t += 2) {
;             const bool last = (t == nt - 2);
;             const char* a1 = cA + (size_t)(t + 1) * kstep;
;             const char* a2 = last ? nA : cA + (size_t)(t + 2) * kstep; const char* b2 = last ? nB : cB + (size_t)(t + 2) * kstep;
;             const char* a3 = a2 + kstep; const char* b3 = b2 + kstep;
.LBB0_1126:
	s_ashr_i32 s25, s24, 31
	s_lshl_b64 s[26:27], s[24:25], 21
	s_add_u32 s36, s54, s26
	s_addc_u32 s37, s55, s27
	s_and_b64 s[26:27], s[4:5], exec
	s_cselect_b32 s25, s37, s41
	s_cselect_b32 s26, s36, s40
	s_ashr_i32 s23, s22, 31
	s_lshl_b64 s[34:35], s[22:23], 21
	s_add_u32 s38, s19, s34
	s_addc_u32 s39, s21, s35
	s_and_b64 s[34:35], s[4:5], exec
	s_cselect_b32 s23, s39, s43
	s_cselect_b32 s27, s38, s42
	s_add_u32 s40, s40, 0x100080
	s_addc_u32 s41, s41, 0
	s_add_u32 s45, s42, 0x100
	s_addc_u32 s52, s43, 0
	s_mov_b32 s53, -2
	v_readfirstlane_b32 s98, v0
	s_nop 1
	s_cmpk_gt_u32 s98, 0x7f
	s_cbranch_scc1 .Lp11_st_skip
	s_lshl_b32 s98, s6, 11
	s_add_u32 s100, s8, s98
	s_addc_u32 s101, s9, 0
	v_lshlrev_b32_e32 v232, 4, v0
	global_load_dwordx4 v[228:231], v232, s[100:101]

; #define PG8_STAGE(bufoff, gbase, voff) do { _Pragma("unroll") for (int _i = 0; _i < 2; ++_i) \
;         __builtin_amdgcn_global_load_lds((const unsigned*)((const char*)(gbase) + (voff)[_i]), (PG8_LAS unsigned*)(lds + (bufoff) + ldsw + _i * 8192), 16, 0, 0); } while (0)
; #define PG8_LDA(dst, b, h) do { _Pragma("unroll") for (int m = 0; m < 4; ++m) _Pragma("unroll") for (int k = 0; k < 2; ++k) dst[m][k] = *(const PG8_LAS bf16x8*)(lds + PG8_SA(b, h) + aoff + m * 2048 + k * 1024); } while (0)
; #define PG8_LDB(dst, b, h) do { _Pragma("unroll") for (int n = 0; n < 2; ++n) _Pragma("unroll") for (int k = 0; k < 2; ++k) dst[n][k] = *(const PG8_LAS bf16x8*)(lds + PG8_SB(b, h) + boff + n * 2048 + k * 1024); } while (0)
; #define PG8_MMA(ai, bj, At, Bt) do { __builtin_amdgcn_s_setprio(1); _Pragma("unroll") for (int m = 0; m < 4; ++m) _Pragma("unroll") for (int n = 0; n < 2; ++n) _Pragma("unroll") for (int k = 0; k < 2; ++k) \
;         acc[ai][bj][m][n] = __builtin_amdgcn_mfma_f32_16x16x32_bf16(Bt[n][k], At[m][k], acc[ai][bj][m][n], 0, 0, 0); __builtin_amdgcn_s_setprio(0); } while (0)
; #define PG8_WAIT_V(n) asm volatile("s_waitcnt vmcnt(" #n ")" ::: "memory")
; #define PG8_WAIT_L(n) asm volatile("s_waitcnt lgkmcnt(" #n ")" ::: "memory")
; #define PG8_BAR __builtin_amdgcn_s_barrier()
; #define PG8_SCHED __builtin_amdgcn_sched_barrier(0)
; template <class Epi, class Sched, bool ALIGN_EPI = false, bool SP2 = false>
; __device__ __forceinline__ void gemm_phase(PG8_LAS unsigned char* lds, const Gemm g, const Sched& S, const Epi& E) {
;     ...
;             PG8_LDB(B0, 0, 0); PG8_LDB(B1, 0, 1); PG8_SCHED; PG8_LDA(At, 0, 0); PG8_STAGE(PG8_SA(1, 1), a1 + hstepA, voffA);
;             PG8_WAIT_V(8); PG8_WAIT_L(0); PG8_BAR; PG8_MMA(0, 0, At, B0); PG8_MMA(0, 1, At, B1); PG8_BAR; PG8_SCHED;
;             PG8_LDA(At, 0, 1); PG8_STAGE(PG8_SB(0, 0), b2, voffB); PG8_STAGE(PG8_SB(0, 1), b2 + hstepB, voffB); PG8_STAGE(PG8_SA(0, 0), a2, voffA);
;             PG8_WAIT_V(8); PG8_WAIT_L(0); PG8_BAR; PG8_MMA(1, 0, At, B0); PG8_MMA(1, 1, At, B1); PG8_BAR; PG8_SCHED;
.Lsp_LBB0_1127:
	ds_read_b128 v[130:133], v203
	ds_read_b128 v[134:137], v203 offset:1024
	ds_read_b128 v[138:141], v203 offset:2048
	ds_read_b128 v[142:145], v203 offset:3072
	ds_read_b128 v[146:149], v205
	ds_read_b128 v[150:153], v205 offset:1024
	ds_read_b128 v[154:157], v205 offset:2048
	ds_read_b128 v[158:161], v205 offset:3072
	s_add_u32 s34, s40, 0xfff00080
	s_addc_u32 s35, s41, -1
	s_cmp_eq_u32 s53, 60
	s_cselect_b32 s35, s25, s35
	s_cselect_b32 s34, s26, s34
	s_cselect_b32 s43, s23, s52
	s_cselect_b32 s42, s27, s45
	s_add_i32 m0, s47, 0xc000
	ds_read_b128 v[162:165], v207
	ds_read_b128 v[166:169], v207 offset:1024
	ds_read_b128 v[170:173], v207 offset:2048
	ds_read_b128 v[174:177], v207 offset:3072
	ds_read_b128 v[196:199], v207 offset:4096
	ds_read_b128 v[208:211], v207 offset:5120
	ds_read_b128 v[212:215], v207 offset:6144
	ds_read_b128 v[216:219], v207 offset:7168
	global_load_lds_dwordx4 v188, s[40:41]
	s_add_i32 m0, s47, 0xe000
	s_nop 0
	global_load_lds_dwordx4 v190, s[40:41]
	s_waitcnt vmcnt(8)
	s_waitcnt lgkmcnt(0)
	s_barrier
	s_waitcnt lgkmcnt(0)
	v_mfma_f32_16x16x32_bf16 v[122:125], v[130:133], v[162:165], 0
	v_mfma_f32_16x16x32_bf16 v[118:121], v[138:141], v[162:165], 0
	v_mfma_f32_16x16x32_bf16 v[106:109], v[130:133], v[170:173], 0
	v_mfma_f32_16x16x32_bf16 v[102:105], v[138:141], v[170:173], 0
	v_mfma_f32_16x16x32_bf16 v[90:93], v[130:133], v[196:199], 0
	v_mfma_f32_16x16x32_bf16 v[86:89], v[138:141], v[196:199], 0
	v_mfma_f32_16x16x32_bf16 v[74:77], v[130:133], v[212:215], 0
	v_mfma_f32_16x16x32_bf16 v[70:73], v[138:141], v[212:215], 0
	v_mfma_f32_16x16x32_bf16 v[122:125], v[134:137], v[166:169], v[122:125]
	v_mfma_f32_16x16x32_bf16 v[118:121], v[142:145], v[166:169], v[118:121]
	v_mfma_f32_16x16x32_bf16 v[106:109], v[134:137], v[174:177], v[106:109]
	v_mfma_f32_16x16x32_bf16 v[102:105], v[142:145], v[174:177], v[102:105]
	v_mfma_f32_16x16x32_bf16 v[90:93], v[134:137], v[208:211], v[90:93]
	v_mfma_f32_16x16x32_bf16 v[86:89], v[142:145], v[208:211], v[86:89]
	v_mfma_f32_16x16x32_bf16 v[74:77], v[134:137], v[216:219], v[74:77]
	v_mfma_f32_16x16x32_bf16 v[70:73], v[142:145], v[216:219], v[70:73]
	v_mfma_f32_16x16x32_bf16 v[126:129], v[146:149], v[162:165], 0
	v_mfma_f32_16x16x32_bf16 v[114:117], v[154:157], v[162:165], 0
	v_mfma_f32_16x16x32_bf16 v[110:113], v[146:149], v[170:173], 0
	v_mfma_f32_16x16x32_bf16 v[98:101], v[154:157], v[170:173], 0
	v_mfma_f32_16x16x32_bf16 v[94:97], v[146:149], v[196:199], 0
	v_mfma_f32_16x16x32_bf16 v[82:85], v[154:157], v[196:199], 0
	v_mfma_f32_16x16x32_bf16 v[78:81], v[146:149], v[212:215], 0
	v_mfma_f32_16x16x32_bf16 v[66:69], v[154:157], v[212:215], 0
	v_mfma_f32_16x16x32_bf16 v[126:129], v[150:153], v[166:169], v[126:129]
	v_mfma_f32_16x16x32_bf16 v[114:117], v[158:161], v[166:169], v[114:117]
	v_mfma_f32_16x16x32_bf16 v[110:113], v[150:153], v[174:177], v[110:113]
	v_mfma_f32_16x16x32_bf16 v[98:101], v[158:161], v[174:177], v[98:101]
	v_mfma_f32_16x16x32_bf16 v[94:97], v[150:153], v[208:211], v[94:97]
	v_mfma_f32_16x16x32_bf16 v[82:85], v[158:161], v[208:211], v[82:85]
	v_mfma_f32_16x16x32_bf16 v[78:81], v[150:153], v[216:219], v[78:81]
	v_mfma_f32_16x16x32_bf16 v[66:69], v[158:161], v[216:219], v[66:69]
	s_barrier
	s_add_i32 s73, s68, s17
	s_add_u32 s98, s42, 0x80
	s_addc_u32 s99, s43, 0
	s_add_u32 s100, s34, 0x80
	s_addc_u32 s101, s35, 0
	s_mov_b32 m0, s73
	ds_read_b128 v[162:165], v207 offset:16384
	ds_read_b128 v[166:169], v207 offset:17408
	ds_read_b128 v[170:173], v207 offset:18432
	ds_read_b128 v[174:177], v207 offset:19456
	ds_read_b128 v[196:199], v207 offset:20480
	ds_read_b128 v[208:211], v207 offset:21504
	ds_read_b128 v[212:215], v207 offset:22528
	ds_read_b128 v[216:219], v207 offset:23552
	global_load_lds_dwordx4 v182, s[42:43]
	s_add_i32 m0, s73, 0x2000
	s_add_u32 s74, s42, 0x100000
	s_addc_u32 s75, s43, 0
	s_add_i32 s73, s69, s17
	global_load_lds_dwordx4 v178, s[42:43]
	s_mov_b32 m0, s73
	s_nop 0
	global_load_lds_dwordx4 v182, s[74:75]
	s_add_i32 m0, s73, 0x2000
	s_nop 0
	global_load_lds_dwordx4 v178, s[74:75]
	s_mov_b32 m0, s47
	s_nop 0
	global_load_lds_dwordx4 v184, s[34:35]
	s_mov_b32 m0, s48
	s_nop 0
	global_load_lds_dwordx4 v180, s[34:35]
	s_waitcnt vmcnt(8)
	s_waitcnt lgkmcnt(0)
	s_barrier
	s_waitcnt lgkmcnt(0)
	v_mfma_f32_16x16x32_bf16 v[58:61], v[130:133], v[162:165], 0
	v_mfma_f32_16x16x32_bf16 v[54:57], v[138:141], v[162:165], 0
	v_mfma_f32_16x16x32_bf16 v[42:45], v[130:133], v[170:173], 0
	v_mfma_f32_16x16x32_bf16 v[38:41], v[138:141], v[170:173], 0
	v_mfma_f32_16x16x32_bf16 v[26:29], v[130:133], v[196:199], 0
	v_mfma_f32_16x16x32_bf16 v[22:25], v[138:141], v[196:199], 0
	v_mfma_f32_16x16x32_bf16 v[10:13], v[130:133], v[212:215], 0
	v_mfma_f32_16x16x32_bf16 v[6:9], v[138:141], v[212:215], 0
	v_mfma_f32_16x16x32_bf16 v[58:61], v[134:137], v[166:169], v[58:61]
	v_mfma_f32_16x16x32_bf16 v[54:57], v[142:145], v[166:169], v[54:57]
	v_mfma_f32_16x16x32_bf16 v[42:45], v[134:137], v[174:177], v[42:45]
	v_mfma_f32_16x16x32_bf16 v[38:41], v[142:145], v[174:177], v[38:41]
	v_mfma_f32_16x16x32_bf16 v[26:29], v[134:137], v[208:211], v[26:29]
	v_mfma_f32_16x16x32_bf16 v[22:25], v[142:145], v[208:211], v[22:25]
	v_mfma_f32_16x16x32_bf16 v[10:13], v[134:137], v[216:219], v[10:13]
	v_mfma_f32_16x16x32_bf16 v[6:9], v[142:145], v[216:219], v[6:9]
	v_mfma_f32_16x16x32_bf16 v[62:65], v[146:149], v[162:165], 0
	v_mfma_f32_16x16x32_bf16 v[50:53], v[154:157], v[162:165], 0
	v_mfma_f32_16x16x32_bf16 v[46:49], v[146:149], v[170:173], 0
	v_mfma_f32_16x16x32_bf16 v[34:37], v[154:157], v[170:173], 0
	v_mfma_f32_16x16x32_bf16 v[30:33], v[146:149], v[196:199], 0
	v_mfma_f32_16x16x32_bf16 v[18:21], v[154:157], v[196:199], 0
	v_mfma_f32_16x16x32_bf16 v[14:17], v[146:149], v[212:215], 0
	v_mfma_f32_16x16x32_bf16 v[2:5], v[154:157], v[212:215], 0
	v_mfma_f32_16x16x32_bf16 v[62:65], v[150:153], v[166:169], v[62:65]
	v_mfma_f32_16x16x32_bf16 v[50:53], v[158:161], v[166:169], v[50:53]
	v_mfma_f32_16x16x32_bf16 v[46:49], v[150:153], v[174:177], v[46:49]
	v_mfma_f32_16x16x32_bf16 v[34:37], v[158:161], v[174:177], v[34:37]
	v_mfma_f32_16x16x32_bf16 v[30:33], v[150:153], v[208:211], v[30:33]
	v_mfma_f32_16x16x32_bf16 v[18:21], v[158:161], v[208:211], v[18:21]
	v_mfma_f32_16x16x32_bf16 v[14:17], v[150:153], v[216:219], v[14:17]
	v_mfma_f32_16x16x32_bf16 v[2:5], v[158:161], v[216:219], v[2:5]
	s_barrier
; #define PG8_STAGE(bufoff, gbase, voff) do { _Pragma("unroll") for (int _i = 0; _i < 2; ++_i) \
;         __builtin_amdgcn_global_load_lds((const unsigned*)((const char*)(gbase) + (voff)[_i]), (PG8_LAS unsigned*)(lds + (bufoff) + ldsw + _i * 8192), 16, 0, 0); } while (0)
; #define PG8_LDA(dst, b, h) do { _Pragma("unroll") for (int m = 0; m < 4; ++m) _Pragma("unroll") for (int k = 0; k < 2; ++k) dst[m][k] = *(const PG8_LAS bf16x8*)(lds + PG8_SA(b, h) + aoff + m * 2048 + k * 1024); } while (0)
; #define PG8_LDB(dst, b, h) do { _Pragma("unroll") for (int n = 0; n < 2; ++n) _Pragma("unroll") for (int k = 0; k < 2; ++k) dst[n][k] = *(const PG8_LAS bf16x8*)(lds + PG8_SB(b, h) + boff + n * 2048 + k * 1024); } while (0)
; #define PG8_MMA(ai, bj, At, Bt) do { __builtin_amdgcn_s_setprio(1); _Pragma("unroll") for (int m = 0; m < 4; ++m) _Pragma("unroll") for (int n = 0; n < 2; ++n) _Pragma("unroll") for (int k = 0; k < 2; ++k) \
;         acc[ai][bj][m][n] = __builtin_amdgcn_mfma_f32_16x16x32_bf16(Bt[n][k], At[m][k], acc[ai][bj][m][n], 0, 0, 0); __builtin_amdgcn_s_setprio(0); } while (0)
; #define PG8_WAIT_V(n) asm volatile("s_waitcnt vmcnt(" #n ")" ::: "memory")
; #define PG8_WAIT_L(n) asm volatile("s_waitcnt lgkmcnt(" #n ")" ::: "memory")
; #define PG8_BAR __builtin_amdgcn_s_barrier()
; #define PG8_SCHED __builtin_amdgcn_sched_barrier(0)
; template <class Epi, class Sched, bool ALIGN_EPI = false, bool SP2 = false>
; __device__ __forceinline__ void gemm_phase(PG8_LAS unsigned char* lds, const Gemm g, const Sched& S, const Epi& E) {
;     ...
;             PG8_LDB(B0, 1, 0); PG8_LDB(B1, 1, 1); PG8_SCHED; PG8_LDA(At, 1, 0); PG8_STAGE(PG8_SA(0, 1), a2 + hstepA, voffA);
;             PG8_WAIT_V(8); PG8_WAIT_L(0); PG8_BAR; PG8_MMA(0, 0, At, B0); PG8_MMA(0, 1, At, B1); PG8_BAR; PG8_SCHED;
;             PG8_LDA(At, 1, 1); PG8_STAGE(PG8_SB(1, 0), b3, voffB); PG8_STAGE(PG8_SB(1, 1), b3 + hstepB, voffB); PG8_STAGE(PG8_SA(1, 0), a3, voffA);
;             PG8_WAIT_V(8); PG8_WAIT_L(0); PG8_BAR; PG8_MMA(1, 0, At, B0); PG8_MMA(1, 1, At, B1); PG8_BAR; PG8_SCHED;
	s_add_i32 s73, 0, 0x18000
	s_add_i32 s74, 0, 0x1c000
	v_add_u32_e32 v142, s73, v1
	v_add_u32_e32 v158, s74, v1
	ds_read_b128 v[130:133], v142
	ds_read_b128 v[134:137], v142 offset:1024
	ds_read_b128 v[138:141], v142 offset:2048
	ds_read_b128 v[142:145], v142 offset:3072
	ds_read_b128 v[146:149], v158
	ds_read_b128 v[150:153], v158 offset:1024
	ds_read_b128 v[154:157], v158 offset:2048
	ds_read_b128 v[158:161], v158 offset:3072
	s_add_u32 s34, s34, 0x100000
	s_addc_u32 s35, s35, 0
	s_mov_b32 m0, s49
	ds_read_b128 v[162:165], v207 offset:32768
	ds_read_b128 v[166:169], v207 offset:33792
	ds_read_b128 v[170:173], v207 offset:34816
	ds_read_b128 v[174:177], v207 offset:35840
	ds_read_b128 v[196:199], v207 offset:36864
	ds_read_b128 v[208:211], v207 offset:37888
	ds_read_b128 v[212:215], v207 offset:38912
	ds_read_b128 v[216:219], v207 offset:39936
	global_load_lds_dwordx4 v184, s[34:35]
	s_mov_b32 m0, s60
	s_nop 0
	global_load_lds_dwordx4 v180, s[34:35]
	s_waitcnt vmcnt(8)
	s_waitcnt lgkmcnt(0)
	s_barrier
	s_waitcnt lgkmcnt(0)
	v_mfma_f32_16x16x32_bf16 v[122:125], v[130:133], v[162:165], v[122:125]
	v_mfma_f32_16x16x32_bf16 v[118:121], v[138:141], v[162:165], v[118:121]
	v_mfma_f32_16x16x32_bf16 v[106:109], v[130:133], v[170:173], v[106:109]
	v_mfma_f32_16x16x32_bf16 v[102:105], v[138:141], v[170:173], v[102:105]
	v_mfma_f32_16x16x32_bf16 v[90:93], v[130:133], v[196:199], v[90:93]
	v_mfma_f32_16x16x32_bf16 v[86:89], v[138:141], v[196:199], v[86:89]
	v_mfma_f32_16x16x32_bf16 v[74:77], v[130:133], v[212:215], v[74:77]
	v_mfma_f32_16x16x32_bf16 v[70:73], v[138:141], v[212:215], v[70:73]
	v_mfma_f32_16x16x32_bf16 v[122:125], v[134:137], v[166:169], v[122:125]
	v_mfma_f32_16x16x32_bf16 v[118:121], v[142:145], v[166:169], v[118:121]
	v_mfma_f32_16x16x32_bf16 v[106:109], v[134:137], v[174:177], v[106:109]
	v_mfma_f32_16x16x32_bf16 v[102:105], v[142:145], v[174:177], v[102:105]
	v_mfma_f32_16x16x32_bf16 v[90:93], v[134:137], v[208:211], v[90:93]
	v_mfma_f32_16x16x32_bf16 v[86:89], v[142:145], v[208:211], v[86:89]
	v_mfma_f32_16x16x32_bf16 v[74:77], v[134:137], v[216:219], v[74:77]
	v_mfma_f32_16x16x32_bf16 v[70:73], v[142:145], v[216:219], v[70:73]
	v_mfma_f32_16x16x32_bf16 v[126:129], v[146:149], v[162:165], v[126:129]
	v_mfma_f32_16x16x32_bf16 v[114:117], v[154:157], v[162:165], v[114:117]
	v_mfma_f32_16x16x32_bf16 v[110:113], v[146:149], v[170:173], v[110:113]
	v_mfma_f32_16x16x32_bf16 v[98:101], v[154:157], v[170:173], v[98:101]
	v_mfma_f32_16x16x32_bf16 v[94:97], v[146:149], v[196:199], v[94:97]
	v_mfma_f32_16x16x32_bf16 v[82:85], v[154:157], v[196:199], v[82:85]
	v_mfma_f32_16x16x32_bf16 v[78:81], v[146:149], v[212:215], v[78:81]
	v_mfma_f32_16x16x32_bf16 v[66:69], v[154:157], v[212:215], v[66:69]
	v_mfma_f32_16x16x32_bf16 v[126:129], v[150:153], v[166:169], v[126:129]
	v_mfma_f32_16x16x32_bf16 v[114:117], v[158:161], v[166:169], v[114:117]
	v_mfma_f32_16x16x32_bf16 v[110:113], v[150:153], v[174:177], v[110:113]
	v_mfma_f32_16x16x32_bf16 v[98:101], v[158:161], v[174:177], v[98:101]
	v_mfma_f32_16x16x32_bf16 v[94:97], v[150:153], v[208:211], v[94:97]
	v_mfma_f32_16x16x32_bf16 v[82:85], v[158:161], v[208:211], v[82:85]
	v_mfma_f32_16x16x32_bf16 v[78:81], v[150:153], v[216:219], v[78:81]
	v_mfma_f32_16x16x32_bf16 v[66:69], v[158:161], v[216:219], v[66:69]
	s_barrier
	s_add_i32 s34, s73, s17
	s_mov_b32 m0, s34
	ds_read_b128 v[162:165], v207 offset:49152
	ds_read_b128 v[166:169], v207 offset:50176
	ds_read_b128 v[170:173], v207 offset:51200
	ds_read_b128 v[174:177], v207 offset:52224
	ds_read_b128 v[196:199], v207 offset:53248
	ds_read_b128 v[208:211], v207 offset:54272
	ds_read_b128 v[212:215], v207 offset:55296
	ds_read_b128 v[216:219], v207 offset:56320
	global_load_lds_dwordx4 v182, s[98:99]
	s_add_i32 m0, s34, 0x2000
	s_add_u32 s34, s42, 0x100080
	s_addc_u32 s35, s43, 0
	s_add_i32 s42, s74, s17
	global_load_lds_dwordx4 v178, s[98:99]
	s_mov_b32 m0, s42
	s_nop 0
	global_load_lds_dwordx4 v182, s[34:35]
	s_add_i32 m0, s42, 0x2000
	s_nop 0
	global_load_lds_dwordx4 v178, s[34:35]
	s_mov_b32 m0, s64
	s_nop 0
	global_load_lds_dwordx4 v184, s[100:101]
	s_mov_b32 m0, s65
	s_nop 0
	global_load_lds_dwordx4 v180, s[100:101]
	s_waitcnt vmcnt(8)
	s_waitcnt lgkmcnt(0)
	s_barrier
	s_waitcnt lgkmcnt(0)
	v_mfma_f32_16x16x32_bf16 v[58:61], v[130:133], v[162:165], v[58:61]
	v_mfma_f32_16x16x32_bf16 v[54:57], v[138:141], v[162:165], v[54:57]
	v_mfma_f32_16x16x32_bf16 v[42:45], v[130:133], v[170:173], v[42:45]
	v_mfma_f32_16x16x32_bf16 v[38:41], v[138:141], v[170:173], v[38:41]
	v_mfma_f32_16x16x32_bf16 v[26:29], v[130:133], v[196:199], v[26:29]
	v_mfma_f32_16x16x32_bf16 v[22:25], v[138:141], v[196:199], v[22:25]
	v_mfma_f32_16x16x32_bf16 v[10:13], v[130:133], v[212:215], v[10:13]
	v_mfma_f32_16x16x32_bf16 v[6:9], v[138:141], v[212:215], v[6:9]
	v_mfma_f32_16x16x32_bf16 v[58:61], v[134:137], v[166:169], v[58:61]
	v_mfma_f32_16x16x32_bf16 v[54:57], v[142:145], v[166:169], v[54:57]
	v_mfma_f32_16x16x32_bf16 v[42:45], v[134:137], v[174:177], v[42:45]
	v_mfma_f32_16x16x32_bf16 v[38:41], v[142:145], v[174:177], v[38:41]
	v_mfma_f32_16x16x32_bf16 v[26:29], v[134:137], v[208:211], v[26:29]
	v_mfma_f32_16x16x32_bf16 v[22:25], v[142:145], v[208:211], v[22:25]
	v_mfma_f32_16x16x32_bf16 v[10:13], v[134:137], v[216:219], v[10:13]
	v_mfma_f32_16x16x32_bf16 v[6:9], v[142:145], v[216:219], v[6:9]
	v_mfma_f32_16x16x32_bf16 v[62:65], v[146:149], v[162:165], v[62:65]
	v_mfma_f32_16x16x32_bf16 v[50:53], v[154:157], v[162:165], v[50:53]
	v_mfma_f32_16x16x32_bf16 v[46:49], v[146:149], v[170:173], v[46:49]
	v_mfma_f32_16x16x32_bf16 v[34:37], v[154:157], v[170:173], v[34:37]
	v_mfma_f32_16x16x32_bf16 v[30:33], v[146:149], v[196:199], v[30:33]
	v_mfma_f32_16x16x32_bf16 v[18:21], v[154:157], v[196:199], v[18:21]
	v_mfma_f32_16x16x32_bf16 v[14:17], v[146:149], v[212:215], v[14:17]
	v_mfma_f32_16x16x32_bf16 v[2:5], v[154:157], v[212:215], v[2:5]
	v_mfma_f32_16x16x32_bf16 v[62:65], v[150:153], v[166:169], v[62:65]
	v_mfma_f32_16x16x32_bf16 v[50:53], v[158:161], v[166:169], v[50:53]
	v_mfma_f32_16x16x32_bf16 v[46:49], v[150:153], v[174:177], v[46:49]
	v_mfma_f32_16x16x32_bf16 v[34:37], v[158:161], v[174:177], v[34:37]
	v_mfma_f32_16x16x32_bf16 v[30:33], v[150:153], v[208:211], v[30:33]
	v_mfma_f32_16x16x32_bf16 v[18:21], v[158:161], v[208:211], v[18:21]
	v_mfma_f32_16x16x32_bf16 v[14:17], v[150:153], v[216:219], v[14:17]
	v_mfma_f32_16x16x32_bf16 v[2:5], v[158:161], v[216:219], v[2:5]
	s_barrier
	s_add_i32 s53, s53, 2
	s_add_u32 s40, s40, 0x100
	s_addc_u32 s41, s41, 0
	s_add_u32 s45, s45, 0x100
	s_addc_u32 s52, s52, 0
	s_cmp_gt_u32 s53, 61

; #define PG8_STAGE(bufoff, gbase, voff) do { _Pragma("unroll") for (int _i = 0; _i < 2; ++_i) \
;         __builtin_amdgcn_global_load_lds((const unsigned*)((const char*)(gbase) + (voff)[_i]), (PG8_LAS unsigned*)(lds + (bufoff) + ldsw + _i * 8192), 16, 0, 0); } while (0)
; #define PG8_LDA(dst, b, h) do { _Pragma("unroll") for (int m = 0; m < 4; ++m) _Pragma("unroll") for (int k = 0; k < 2; ++k) dst[m][k] = *(const PG8_LAS bf16x8*)(lds + PG8_SA(b, h) + aoff + m * 2048 + k * 1024); } while (0)
; #define PG8_LDB(dst, b, h) do { _Pragma("unroll") for (int n = 0; n < 2; ++n) _Pragma("unroll") for (int k = 0; k < 2; ++k) dst[n][k] = *(const PG8_LAS bf16x8*)(lds + PG8_SB(b, h) + boff + n * 2048 + k * 1024); } while (0)
; #define PG8_MMA(ai, bj, At, Bt) do { __builtin_amdgcn_s_setprio(1); _Pragma("unroll") for (int m = 0; m < 4; ++m) _Pragma("unroll") for (int n = 0; n < 2; ++n) _Pragma("unroll") for (int k = 0; k < 2; ++k) \
;         acc[ai][bj][m][n] = __builtin_amdgcn_mfma_f32_16x16x32_bf16(Bt[n][k], At[m][k], acc[ai][bj][m][n], 0, 0, 0); __builtin_amdgcn_s_setprio(0); } while (0)
; #define PG8_WAIT_V(n) asm volatile("s_waitcnt vmcnt(" #n ")" ::: "memory")
; #define PG8_WAIT_L(n) asm volatile("s_waitcnt lgkmcnt(" #n ")" ::: "memory")
; #define PG8_BAR __builtin_amdgcn_s_barrier()
; #define PG8_SCHED __builtin_amdgcn_sched_barrier(0)
; template <class Epi, class Sched, bool ALIGN_EPI = false, bool SP2 = false>
; __device__ __forceinline__ void gemm_phase(PG8_LAS unsigned char* lds, const Gemm g, const Sched& S, const Epi& E) {
;     ...
;             const char* a2 = last ? nA : cA + (size_t)(t + 2) * kstep; const char* b2 = last ? nB : cB + (size_t)(t + 2) * kstep;
;             const char* a3 = a2 + kstep; const char* b3 = b2 + kstep;
;             if (last && has_next) S.a_ready(nxt);
;             if constexpr (SP2) {
;             PG8_LDB(B0, 0, 0); PG8_LDB(B1, 0, 1); PG8_SCHED; PG8_LDA(At, 0, 0); PG8_STAGE(PG8_SA(1, 1), a1 + hstepA, voffA);
;             PG8_WAIT_V(8); PG8_WAIT_L(0); PG8_BAR; PG8_MMA(0, 0, At, B0); PG8_MMA(0, 1, At, B1); PG8_BAR; PG8_SCHED;
;             PG8_LDA(At, 0, 1); PG8_STAGE(PG8_SB(0, 0), b2, voffB); PG8_STAGE(PG8_SB(0, 1), b2 + hstepB, voffB); PG8_STAGE(PG8_SA(0, 0), a2, voffA);
;             PG8_WAIT_V(8); PG8_WAIT_L(0); PG8_BAR; PG8_MMA(1, 0, At, B0); PG8_MMA(1, 1, At, B1); PG8_BAR; PG8_SCHED;
.LBB0_1205:
	s_add_u32 s62, s36, 0x100
	s_addc_u32 s63, s37, 0
	s_mov_b32 s64, -2
	s_setprio 1
	s_cmp_eq_u64 s[12:13], 0
	s_cbranch_scc1 .Lsp_LBB0_1206
	s_setprio 0
.Lsp_LBB0_1206:
	ds_read_b128 v[130:133], v166
	ds_read_b128 v[134:137], v166 offset:1024
	ds_read_b128 v[138:141], v166 offset:2048
	ds_read_b128 v[142:145], v166 offset:3072
	ds_read_b128 v[170:173], v167
	ds_read_b128 v[174:177], v167 offset:1024
	ds_read_b128 v[178:181], v167 offset:2048
	ds_read_b128 v[182:185], v167 offset:3072
	s_add_u32 s36, s24, 0x100
	s_addc_u32 s37, s25, 0
	s_cmpk_eq_i32 s64, 0xbc
	s_cselect_b32 s35, s7, s37
	s_cselect_b32 s34, s6, s36
	s_cselect_b32 s39, s23, s63
	s_cselect_b32 s38, s22, s62
	s_add_i32 m0, s27, 0xc000
	ds_read_b128 v[186:189], v168
	ds_read_b128 v[190:193], v168 offset:1024
	ds_read_b128 v[194:197], v168 offset:2048
	ds_read_b128 v[198:201], v168 offset:3072
	ds_read_b128 v[202:205], v168 offset:4096
	ds_read_b128 v[206:209], v168 offset:5120
	ds_read_b128 v[210:213], v168 offset:6144
	ds_read_b128 v[214:217], v168 offset:7168
	global_load_lds_dwordx4 v154, s[24:25]
	s_add_i32 m0, s27, 0xe000
	s_nop 0
	global_load_lds_dwordx4 v156, s[24:25]
	s_waitcnt vmcnt(8)
	s_waitcnt lgkmcnt(0)
	s_barrier
	s_waitcnt lgkmcnt(0)
	v_mfma_f32_16x16x32_bf16 v[126:129], v[130:133], v[186:189], 0
	v_mfma_f32_16x16x32_bf16 v[122:125], v[138:141], v[186:189], 0
	v_mfma_f32_16x16x32_bf16 v[118:121], v[130:133], v[194:197], 0
	v_mfma_f32_16x16x32_bf16 v[114:117], v[138:141], v[194:197], 0
	v_mfma_f32_16x16x32_bf16 v[110:113], v[130:133], v[202:205], 0
	v_mfma_f32_16x16x32_bf16 v[102:105], v[138:141], v[202:205], 0
	v_mfma_f32_16x16x32_bf16 v[94:97], v[130:133], v[210:213], 0
	v_mfma_f32_16x16x32_bf16 v[86:89], v[138:141], v[210:213], 0
	v_mfma_f32_16x16x32_bf16 v[126:129], v[134:137], v[190:193], v[126:129]
	v_mfma_f32_16x16x32_bf16 v[122:125], v[142:145], v[190:193], v[122:125]
	v_mfma_f32_16x16x32_bf16 v[118:121], v[134:137], v[198:201], v[118:121]
	v_mfma_f32_16x16x32_bf16 v[114:117], v[142:145], v[198:201], v[114:117]
	v_mfma_f32_16x16x32_bf16 v[110:113], v[134:137], v[206:209], v[110:113]
	v_mfma_f32_16x16x32_bf16 v[102:105], v[142:145], v[206:209], v[102:105]
	v_mfma_f32_16x16x32_bf16 v[94:97], v[134:137], v[214:217], v[94:97]
	v_mfma_f32_16x16x32_bf16 v[86:89], v[142:145], v[214:217], v[86:89]
	v_mfma_f32_16x16x32_bf16 v[106:109], v[170:173], v[186:189], 0
	v_mfma_f32_16x16x32_bf16 v[98:101], v[178:181], v[186:189], 0
	v_mfma_f32_16x16x32_bf16 v[90:93], v[170:173], v[194:197], 0
	v_mfma_f32_16x16x32_bf16 v[82:85], v[178:181], v[194:197], 0
	v_mfma_f32_16x16x32_bf16 v[78:81], v[170:173], v[202:205], 0
	v_mfma_f32_16x16x32_bf16 v[74:77], v[178:181], v[202:205], 0
	v_mfma_f32_16x16x32_bf16 v[70:73], v[170:173], v[210:213], 0
	v_mfma_f32_16x16x32_bf16 v[66:69], v[178:181], v[210:213], 0
	v_mfma_f32_16x16x32_bf16 v[106:109], v[174:177], v[190:193], v[106:109]
	v_mfma_f32_16x16x32_bf16 v[98:101], v[182:185], v[190:193], v[98:101]
	v_mfma_f32_16x16x32_bf16 v[90:93], v[174:177], v[198:201], v[90:93]
	v_mfma_f32_16x16x32_bf16 v[82:85], v[182:185], v[198:201], v[82:85]
	v_mfma_f32_16x16x32_bf16 v[78:81], v[174:177], v[206:209], v[78:81]
	v_mfma_f32_16x16x32_bf16 v[74:77], v[182:185], v[206:209], v[74:77]
	v_mfma_f32_16x16x32_bf16 v[70:73], v[174:177], v[214:217], v[70:73]
	v_mfma_f32_16x16x32_bf16 v[66:69], v[182:185], v[214:217], v[66:69]
	s_barrier
	s_add_i32 s24, s48, s26
	s_add_u32 s98, s38, 0x80
	s_addc_u32 s99, s39, 0
	s_add_u32 s100, s34, 0x80
	s_addc_u32 s101, s35, 0
	s_mov_b32 m0, s24
	ds_read_b128 v[186:189], v168 offset:16384
	ds_read_b128 v[190:193], v168 offset:17408
	ds_read_b128 v[194:197], v168 offset:18432
	ds_read_b128 v[198:201], v168 offset:19456
	ds_read_b128 v[202:205], v168 offset:20480
	ds_read_b128 v[206:209], v168 offset:21504
	ds_read_b128 v[210:213], v168 offset:22528
	ds_read_b128 v[214:217], v168 offset:23552
	global_load_lds_dwordx4 v150, s[38:39]
	s_add_i32 m0, s24, 0x2000
	s_add_u32 s24, s38, 0x300000
	s_addc_u32 s25, s39, 0
	s_add_i32 s65, s49, s26
	global_load_lds_dwordx4 v146, s[38:39]
	s_mov_b32 m0, s65
	s_nop 0
	global_load_lds_dwordx4 v150, s[24:25]
	s_add_i32 m0, s65, 0x2000
	s_nop 0
	global_load_lds_dwordx4 v146, s[24:25]
	s_mov_b32 m0, s27
	s_nop 0
	global_load_lds_dwordx4 v152, s[34:35]
	s_mov_b32 m0, s40
	s_nop 0
	global_load_lds_dwordx4 v148, s[34:35]
	s_waitcnt vmcnt(8)
	s_waitcnt lgkmcnt(0)
	s_barrier
	s_waitcnt lgkmcnt(0)
	v_mfma_f32_16x16x32_bf16 v[62:65], v[130:133], v[186:189], 0
	v_mfma_f32_16x16x32_bf16 v[58:61], v[138:141], v[186:189], 0
	v_mfma_f32_16x16x32_bf16 v[50:53], v[130:133], v[194:197], 0
	v_mfma_f32_16x16x32_bf16 v[42:45], v[138:141], v[194:197], 0
	v_mfma_f32_16x16x32_bf16 v[34:37], v[130:133], v[202:205], 0
	v_mfma_f32_16x16x32_bf16 v[26:29], v[138:141], v[202:205], 0
	v_mfma_f32_16x16x32_bf16 v[18:21], v[130:133], v[210:213], 0
	v_mfma_f32_16x16x32_bf16 v[10:13], v[138:141], v[210:213], 0
	v_mfma_f32_16x16x32_bf16 v[62:65], v[134:137], v[190:193], v[62:65]
	v_mfma_f32_16x16x32_bf16 v[58:61], v[142:145], v[190:193], v[58:61]
	v_mfma_f32_16x16x32_bf16 v[50:53], v[134:137], v[198:201], v[50:53]
	v_mfma_f32_16x16x32_bf16 v[42:45], v[142:145], v[198:201], v[42:45]
	v_mfma_f32_16x16x32_bf16 v[34:37], v[134:137], v[206:209], v[34:37]
	v_mfma_f32_16x16x32_bf16 v[26:29], v[142:145], v[206:209], v[26:29]
	v_mfma_f32_16x16x32_bf16 v[18:21], v[134:137], v[214:217], v[18:21]
	v_mfma_f32_16x16x32_bf16 v[10:13], v[142:145], v[214:217], v[10:13]
	v_mfma_f32_16x16x32_bf16 v[54:57], v[170:173], v[186:189], 0
	v_mfma_f32_16x16x32_bf16 v[46:49], v[178:181], v[186:189], 0
	v_mfma_f32_16x16x32_bf16 v[38:41], v[170:173], v[194:197], 0
	v_mfma_f32_16x16x32_bf16 v[30:33], v[178:181], v[194:197], 0
	v_mfma_f32_16x16x32_bf16 v[22:25], v[170:173], v[202:205], 0
	v_mfma_f32_16x16x32_bf16 v[14:17], v[178:181], v[202:205], 0
	v_mfma_f32_16x16x32_bf16 v[6:9], v[170:173], v[210:213], 0
	v_mfma_f32_16x16x32_bf16 v[2:5], v[178:181], v[210:213], 0
	v_mfma_f32_16x16x32_bf16 v[54:57], v[174:177], v[190:193], v[54:57]
	v_mfma_f32_16x16x32_bf16 v[46:49], v[182:185], v[190:193], v[46:49]
	v_mfma_f32_16x16x32_bf16 v[38:41], v[174:177], v[198:201], v[38:41]
	v_mfma_f32_16x16x32_bf16 v[30:33], v[182:185], v[198:201], v[30:33]
	v_mfma_f32_16x16x32_bf16 v[22:25], v[174:177], v[206:209], v[22:25]
	v_mfma_f32_16x16x32_bf16 v[14:17], v[182:185], v[206:209], v[14:17]
	v_mfma_f32_16x16x32_bf16 v[6:9], v[174:177], v[214:217], v[6:9]
	v_mfma_f32_16x16x32_bf16 v[2:5], v[182:185], v[214:217], v[2:5]
	s_barrier
; #define PG8_STAGE(bufoff, gbase, voff) do { _Pragma("unroll") for (int _i = 0; _i < 2; ++_i) \
;         __builtin_amdgcn_global_load_lds((const unsigned*)((const char*)(gbase) + (voff)[_i]), (PG8_LAS unsigned*)(lds + (bufoff) + ldsw + _i * 8192), 16, 0, 0); } while (0)
; #define PG8_LDA(dst, b, h) do { _Pragma("unroll") for (int m = 0; m < 4; ++m) _Pragma("unroll") for (int k = 0; k < 2; ++k) dst[m][k] = *(const PG8_LAS bf16x8*)(lds + PG8_SA(b, h) + aoff + m * 2048 + k * 1024); } while (0)
; #define PG8_LDB(dst, b, h) do { _Pragma("unroll") for (int n = 0; n < 2; ++n) _Pragma("unroll") for (int k = 0; k < 2; ++k) dst[n][k] = *(const PG8_LAS bf16x8*)(lds + PG8_SB(b, h) + boff + n * 2048 + k * 1024); } while (0)
; #define PG8_MMA(ai, bj, At, Bt) do { __builtin_amdgcn_s_setprio(1); _Pragma("unroll") for (int m = 0; m < 4; ++m) _Pragma("unroll") for (int n = 0; n < 2; ++n) _Pragma("unroll") for (int k = 0; k < 2; ++k) \
;         acc[ai][bj][m][n] = __builtin_amdgcn_mfma_f32_16x16x32_bf16(Bt[n][k], At[m][k], acc[ai][bj][m][n], 0, 0, 0); __builtin_amdgcn_s_setprio(0); } while (0)
; #define PG8_WAIT_V(n) asm volatile("s_waitcnt vmcnt(" #n ")" ::: "memory")
; #define PG8_WAIT_L(n) asm volatile("s_waitcnt lgkmcnt(" #n ")" ::: "memory")
; #define PG8_BAR __builtin_amdgcn_s_barrier()
; #define PG8_SCHED __builtin_amdgcn_sched_barrier(0)
; template <class Epi, class Sched, bool ALIGN_EPI = false, bool SP2 = false>
; __device__ __forceinline__ void gemm_phase(PG8_LAS unsigned char* lds, const Gemm g, const Sched& S, const Epi& E) {
;     ...
;             PG8_LDB(B0, 1, 0); PG8_LDB(B1, 1, 1); PG8_SCHED; PG8_LDA(At, 1, 0); PG8_STAGE(PG8_SA(0, 1), a2 + hstepA, voffA);
;             PG8_WAIT_V(8); PG8_WAIT_L(0); PG8_BAR; PG8_MMA(0, 0, At, B0); PG8_MMA(0, 1, At, B1); PG8_BAR; PG8_SCHED;
;             PG8_LDA(At, 1, 1); PG8_STAGE(PG8_SB(1, 0), b3, voffB); PG8_STAGE(PG8_SB(1, 1), b3 + hstepB, voffB); PG8_STAGE(PG8_SA(1, 0), a3, voffA);
;             PG8_WAIT_V(8); PG8_WAIT_L(0); PG8_BAR; PG8_MMA(1, 0, At, B0); PG8_MMA(1, 1, At, B1); PG8_BAR; PG8_SCHED;
	s_add_i32 s65, 0, 0x18000
	s_add_i32 s66, 0, 0x1c000
	v_add_u32_e32 v142, s65, v164
	v_add_u32_e32 v169, s66, v164
	ds_read_b128 v[130:133], v142
	ds_read_b128 v[134:137], v142 offset:1024
	ds_read_b128 v[138:141], v142 offset:2048
	ds_read_b128 v[142:145], v142 offset:3072
	ds_read_b128 v[170:173], v169
	ds_read_b128 v[174:177], v169 offset:1024
	ds_read_b128 v[178:181], v169 offset:2048
	ds_read_b128 v[182:185], v169 offset:3072
	s_add_u32 s24, s34, 0x300000
	s_addc_u32 s25, s35, 0
	s_mov_b32 m0, s41
	ds_read_b128 v[186:189], v168 offset:32768
	ds_read_b128 v[190:193], v168 offset:33792
	ds_read_b128 v[194:197], v168 offset:34816
	ds_read_b128 v[198:201], v168 offset:35840
	ds_read_b128 v[202:205], v168 offset:36864
	ds_read_b128 v[206:209], v168 offset:37888
	ds_read_b128 v[210:213], v168 offset:38912
	ds_read_b128 v[214:217], v168 offset:39936
	global_load_lds_dwordx4 v152, s[24:25]
	s_mov_b32 m0, s42
	s_nop 0
	global_load_lds_dwordx4 v148, s[24:25]
	s_waitcnt vmcnt(8)
	s_waitcnt lgkmcnt(0)
	s_barrier
	s_waitcnt lgkmcnt(0)
	v_mfma_f32_16x16x32_bf16 v[126:129], v[130:133], v[186:189], v[126:129]
	v_mfma_f32_16x16x32_bf16 v[122:125], v[138:141], v[186:189], v[122:125]
	v_mfma_f32_16x16x32_bf16 v[118:121], v[130:133], v[194:197], v[118:121]
	v_mfma_f32_16x16x32_bf16 v[114:117], v[138:141], v[194:197], v[114:117]
	v_mfma_f32_16x16x32_bf16 v[110:113], v[130:133], v[202:205], v[110:113]
	v_mfma_f32_16x16x32_bf16 v[102:105], v[138:141], v[202:205], v[102:105]
	v_mfma_f32_16x16x32_bf16 v[94:97], v[130:133], v[210:213], v[94:97]
	v_mfma_f32_16x16x32_bf16 v[86:89], v[138:141], v[210:213], v[86:89]
	v_mfma_f32_16x16x32_bf16 v[126:129], v[134:137], v[190:193], v[126:129]
	v_mfma_f32_16x16x32_bf16 v[122:125], v[142:145], v[190:193], v[122:125]
	v_mfma_f32_16x16x32_bf16 v[118:121], v[134:137], v[198:201], v[118:121]
	v_mfma_f32_16x16x32_bf16 v[114:117], v[142:145], v[198:201], v[114:117]
	v_mfma_f32_16x16x32_bf16 v[110:113], v[134:137], v[206:209], v[110:113]
	v_mfma_f32_16x16x32_bf16 v[102:105], v[142:145], v[206:209], v[102:105]
	v_mfma_f32_16x16x32_bf16 v[94:97], v[134:137], v[214:217], v[94:97]
	v_mfma_f32_16x16x32_bf16 v[86:89], v[142:145], v[214:217], v[86:89]
	v_mfma_f32_16x16x32_bf16 v[106:109], v[170:173], v[186:189], v[106:109]
	v_mfma_f32_16x16x32_bf16 v[98:101], v[178:181], v[186:189], v[98:101]
	v_mfma_f32_16x16x32_bf16 v[90:93], v[170:173], v[194:197], v[90:93]
	v_mfma_f32_16x16x32_bf16 v[82:85], v[178:181], v[194:197], v[82:85]
	v_mfma_f32_16x16x32_bf16 v[78:81], v[170:173], v[202:205], v[78:81]
	v_mfma_f32_16x16x32_bf16 v[74:77], v[178:181], v[202:205], v[74:77]
	v_mfma_f32_16x16x32_bf16 v[70:73], v[170:173], v[210:213], v[70:73]
	v_mfma_f32_16x16x32_bf16 v[66:69], v[178:181], v[210:213], v[66:69]
	v_mfma_f32_16x16x32_bf16 v[106:109], v[174:177], v[190:193], v[106:109]
	v_mfma_f32_16x16x32_bf16 v[98:101], v[182:185], v[190:193], v[98:101]
	v_mfma_f32_16x16x32_bf16 v[90:93], v[174:177], v[198:201], v[90:93]
	v_mfma_f32_16x16x32_bf16 v[82:85], v[182:185], v[198:201], v[82:85]
	v_mfma_f32_16x16x32_bf16 v[78:81], v[174:177], v[206:209], v[78:81]
	v_mfma_f32_16x16x32_bf16 v[74:77], v[182:185], v[206:209], v[74:77]
	v_mfma_f32_16x16x32_bf16 v[70:73], v[174:177], v[214:217], v[70:73]
	v_mfma_f32_16x16x32_bf16 v[66:69], v[182:185], v[214:217], v[66:69]
	s_barrier
	s_add_i32 s24, s65, s26
	s_mov_b32 m0, s24
	ds_read_b128 v[186:189], v168 offset:49152
	ds_read_b128 v[190:193], v168 offset:50176
	ds_read_b128 v[194:197], v168 offset:51200
	ds_read_b128 v[198:201], v168 offset:52224
	ds_read_b128 v[202:205], v168 offset:53248
	ds_read_b128 v[206:209], v168 offset:54272
	ds_read_b128 v[210:213], v168 offset:55296
	ds_read_b128 v[214:217], v168 offset:56320
	global_load_lds_dwordx4 v150, s[98:99]
	s_add_i32 m0, s24, 0x2000
	s_add_u32 s24, s38, 0x300080
	s_addc_u32 s25, s39, 0
	s_add_i32 s34, s66, s26
	global_load_lds_dwordx4 v146, s[98:99]
	s_mov_b32 m0, s34
	s_nop 0
	global_load_lds_dwordx4 v150, s[24:25]
	s_add_i32 m0, s34, 0x2000
	s_nop 0
	global_load_lds_dwordx4 v146, s[24:25]
	s_mov_b32 m0, s46
	s_nop 0
	global_load_lds_dwordx4 v152, s[100:101]
	s_mov_b32 m0, s47
	s_nop 0
	global_load_lds_dwordx4 v148, s[100:101]
	s_waitcnt vmcnt(8)
	s_waitcnt lgkmcnt(0)
	s_barrier
	s_waitcnt lgkmcnt(0)
	v_mfma_f32_16x16x32_bf16 v[62:65], v[130:133], v[186:189], v[62:65]
	v_mfma_f32_16x16x32_bf16 v[58:61], v[138:141], v[186:189], v[58:61]
	v_mfma_f32_16x16x32_bf16 v[50:53], v[130:133], v[194:197], v[50:53]
	v_mfma_f32_16x16x32_bf16 v[42:45], v[138:141], v[194:197], v[42:45]
	v_mfma_f32_16x16x32_bf16 v[34:37], v[130:133], v[202:205], v[34:37]
	v_mfma_f32_16x16x32_bf16 v[26:29], v[138:141], v[202:205], v[26:29]
	v_mfma_f32_16x16x32_bf16 v[18:21], v[130:133], v[210:213], v[18:21]
	v_mfma_f32_16x16x32_bf16 v[10:13], v[138:141], v[210:213], v[10:13]
	v_mfma_f32_16x16x32_bf16 v[62:65], v[134:137], v[190:193], v[62:65]
	v_mfma_f32_16x16x32_bf16 v[58:61], v[142:145], v[190:193], v[58:61]
	v_mfma_f32_16x16x32_bf16 v[50:53], v[134:137], v[198:201], v[50:53]
	v_mfma_f32_16x16x32_bf16 v[42:45], v[142:145], v[198:201], v[42:45]
	v_mfma_f32_16x16x32_bf16 v[34:37], v[134:137], v[206:209], v[34:37]
	v_mfma_f32_16x16x32_bf16 v[26:29], v[142:145], v[206:209], v[26:29]
	v_mfma_f32_16x16x32_bf16 v[18:21], v[134:137], v[214:217], v[18:21]
	v_mfma_f32_16x16x32_bf16 v[10:13], v[142:145], v[214:217], v[10:13]
	v_mfma_f32_16x16x32_bf16 v[54:57], v[170:173], v[186:189], v[54:57]
	v_mfma_f32_16x16x32_bf16 v[46:49], v[178:181], v[186:189], v[46:49]
	v_mfma_f32_16x16x32_bf16 v[38:41], v[170:173], v[194:197], v[38:41]
	v_mfma_f32_16x16x32_bf16 v[30:33], v[178:181], v[194:197], v[30:33]
	v_mfma_f32_16x16x32_bf16 v[22:25], v[170:173], v[202:205], v[22:25]
	v_mfma_f32_16x16x32_bf16 v[14:17], v[178:181], v[202:205], v[14:17]
	v_mfma_f32_16x16x32_bf16 v[6:9], v[170:173], v[210:213], v[6:9]
	v_mfma_f32_16x16x32_bf16 v[2:5], v[178:181], v[210:213], v[2:5]
	v_mfma_f32_16x16x32_bf16 v[54:57], v[174:177], v[190:193], v[54:57]
	v_mfma_f32_16x16x32_bf16 v[46:49], v[182:185], v[190:193], v[46:49]
	v_mfma_f32_16x16x32_bf16 v[38:41], v[174:177], v[198:201], v[38:41]
	v_mfma_f32_16x16x32_bf16 v[30:33], v[182:185], v[198:201], v[30:33]
	v_mfma_f32_16x16x32_bf16 v[22:25], v[174:177], v[206:209], v[22:25]
	v_mfma_f32_16x16x32_bf16 v[14:17], v[182:185], v[206:209], v[14:17]
	v_mfma_f32_16x16x32_bf16 v[6:9], v[174:177], v[214:217], v[6:9]
	v_mfma_f32_16x16x32_bf16 v[2:5], v[182:185], v[214:217], v[2:5]
	s_barrier
	s_add_i32 s64, s64, 2
	s_add_u32 s62, s62, 0x100
	s_addc_u32 s63, s63, 0
	s_cmpk_gt_u32 s64, 0xbd
	s_mov_b64 s[24:25], s[36:37]
